# FFT output written as one aligned 16B store per token (K-permuted Y + matching gather of out-proj weight rows); local barriers kept
# speedup vs baseline: 1.0306x; 1.0306x over previous
; #define LAS __attribute__((address_space(3)))
; __device__ __forceinline__ unsigned xb_add(unsigned* p, unsigned v) { return __hip_atomic_fetch_add(p, v, __ATOMIC_RELAXED, __HIP_MEMORY_SCOPE_AGENT); }
; __device__ __forceinline__ unsigned xb_xcc_id() { return (unsigned)__builtin_amdgcn_s_getreg((3 << 11) | 20) & 0xFu; }
; __device__ __forceinline__ XcdBarrier xcd_barrier_post(unsigned* bar, volatile LAS unsigned* st) {
;     XcdBarrier b; b.bar = bar; b.x = xb_xcc_id(); b.st = st;
;     if (threadIdx.x == 0) (void)xb_add(&bar[XB_XCNT(b.x)], 1u);
;     return b;
; __global__ void __launch_bounds__(NWAVES * 64, 2) mk_fwd(Args args) {
;     ...
;     for (int u = F.tid; u < (LDS_BYTES - LDSCTL_OFF) / 4; u += NWAVES * 64) ((LAS unsigned*)(F.lds + LDSCTL_OFF))[u] = 0u;
;     __syncthreads();
;     XcdBarrier bar; bar.bar = (unsigned*)(F.ctl + CW_BAR); bar.x = 0; bar.st = nullptr;
;     if (!MK_PER_PHASE) bar = xcd_barrier_post((unsigned*)(F.ctl + CW_BAR), F.MISC + 8);
.LBB0_2:
	v_lshl_add_u32 v1, v0, 2, 0
	v_add_u32_e32 v1, 0x22000, v1
	v_mov_b32_e32 v2, 0
	ds_write2st64_b32 v1, v2, v2 offset1:8
	ds_write2st64_b32 v1, v2, v2 offset0:16 offset1:24
	v_or_b32_e32 v1, 0x800, v0
	s_mov_b64 s[2:3], -1
	s_and_saveexec_b64 s[4:5], s[2:3]
	v_lshl_add_u32 v3, v1, 2, 0
	v_add_u32_e32 v3, 0x22000, v3
	ds_write_b32 v3, v2
	s_or_b64 exec, exec, s[4:5]
	s_load_dwordx2 s[66:67], s[0:1], 0x60
	s_load_dwordx8 s[4:11], s[0:1], 0x40
	s_waitcnt lgkmcnt(0)
	s_and_b32 s98, s76, 63
	s_lshl_b32 s98, s98, 8
	s_add_u32 s98, s98, 0x8000
	s_add_u32 s98, s66, s98
	s_addc_u32 s99, s67, 0
	s_mov_b32 s100, 0
	v_writelane_b32 v252, s4, 3
	s_nop 1
	v_writelane_b32 v252, s5, 4
	v_writelane_b32 v252, s6, 5
	v_writelane_b32 v252, s7, 6
	v_writelane_b32 v252, s8, 7
	v_writelane_b32 v252, s9, 8
	v_writelane_b32 v252, s10, 9
	v_writelane_b32 v252, s11, 10
	s_and_saveexec_b64 s[4:5], s[2:3]
	s_add_i32 s2, 0, 0x22000
	v_lshl_add_u32 v1, v1, 2, s2
	v_mov_b32_e32 v2, 0
	ds_write_b32 v1, v2 offset:2048
	s_or_b64 exec, exec, s[4:5]
	v_or_b32_e32 v1, 0xc00, v0
	v_cmp_gt_u32_e64 s[2:3], 7, 6
	v_cmp_gt_u32_e64 s[6:7], 7, 5
	s_and_saveexec_b64 s[4:5], s[6:7]
	v_lshl_add_u32 v2, v1, 2, 0
	v_add_u32_e32 v2, 0x22000, v2
	v_mov_b32_e32 v3, 0
	ds_write_b32 v2, v3
	s_or_b64 exec, exec, s[4:5]
	s_load_dwordx2 s[56:57], s[0:1], 0x68
	s_and_saveexec_b64 s[4:5], s[2:3]
	s_add_i32 s2, 0, 0x22000
	v_lshl_add_u32 v1, v1, 2, s2
	v_mov_b32_e32 v2, 0
	ds_write_b32 v1, v2 offset:2048
	s_or_b64 exec, exec, s[4:5]
	s_load_dwordx16 s[80:95], s[0:1], 0x0
	s_waitcnt lgkmcnt(0)
	s_barrier
	s_add_u32 s0, s66, 0x4000
	s_getreg_b32 s2, hwreg(HW_REG_XCC_ID, 0, 4)
	s_addc_u32 s1, s67, 0
	s_and_b32 s33, s2, 15
	v_cmp_eq_u32_e64 s[4:5], 0, v0
	s_mov_b64 s[2:3], exec
	s_nop 0
	v_writelane_b32 v252, s4, 11
	s_nop 1
	v_writelane_b32 v252, s5, 12
	s_and_b64 s[4:5], s[2:3], s[4:5]
	s_mov_b64 exec, s[4:5]
	s_cbranch_execz .LBB0_13
	s_mov_b64 s[4:5], exec
	v_mbcnt_lo_u32_b32 v1, s4, 0
	v_mbcnt_hi_u32_b32 v1, s5, v1
	v_cmp_eq_u32_e32 vcc, 0, v1
	s_and_b64 s[6:7], exec, vcc
	s_mov_b64 exec, s[6:7]
	s_cbranch_execz .LBB0_13
	s_lshl_b32 s6, s33, 8
	s_bcnt1_i32_b64 s4, s[4:5]
	v_mov_b32_e32 v1, s6
	v_mov_b32_e32 v2, s4
	global_atomic_add v1, v2, s[0:1] offset:1024
	s_lshl_b32 s6, 1, s33
	v_mov_b32_e32 v3, 0
	v_mov_b32_e32 v4, s6
	global_atomic_or v3, v4, s[98:99] offset:128

; #define LAS __attribute__((address_space(3)))
; template <int N, int LOGN> __device__ __forceinline__ void fft_dif(float (&re)[N], float (&im)[N]) {
; #pragma unroll
;     for (int st = 0; st < LOGN; ++st) { const int len = N >> st, half = len >> 1, step = 32 / len;
; #pragma unroll
;         for (int base = 0; base < N; base += len)
; #pragma unroll
;             for (int j = 0; j < half; ++j) { const int a = base + j, b = a + half;
;                 const float ar = re[a], ai = im[a], br = re[b], bi = im[b]; re[a] = ar + br; im[a] = ai + bi;
;                 const float dr = ar - br, di = ai - bi; const int m = (j * step) & 31;
;                 if (m == 0) { re[b] = dr; im[b] = di; }
;                 else if (m == 8) { re[b] = di; im[b] = -dr; }
;                 else { const float wr = C32[m], ws = C32[(m + 24) & 31]; re[b] = dr * wr + di * ws; im[b] = di * wr - dr * ws; }
;                 asm("" : "+v"(re[a])); asm("" : "+v"(im[a])); asm("" : "+v"(re[b])); asm("" : "+v"(im[b])); } }
; __device__ __forceinline__ void fft_phase(Frame& F, const bf16* Yc, bf16* Y) {
;     ...
;         { const int col = t >> 1; LAS unsigned char* l3 = buf + 16 * (529 * (col >> 4) + 33 * (col & 15)) + 8 * (t & 1);
; #pragma unroll 1
;           for (int c = 0; c < 2; ++c) { float re[32], im[32];
; #pragma unroll
;               for (int qq = 0; qq < 32; ++qq) { const unsigned w = *(const LAS unsigned*)(l3 + 4 * c + 16 * qq); re[qq] = bflo(w); im[qq] = bfhi(w); }
;               fft_dif<32, 5>(re, im);
.LBB0_201:
	v_cndmask_b32_e64 v2, 0, 1, s[4:5]
	v_add_u32_e32 v11, s0, v195
	v_cmp_ne_u32_e32 vcc, 1, v2
	ds_read2_b32 v[2:3], v11 offset1:4
	ds_read2_b32 v[4:5], v11 offset0:8 offset1:12
	ds_read2_b32 v[6:7], v11 offset0:16 offset1:20
	ds_read2_b32 v[8:9], v11 offset0:24 offset1:28
	ds_read2_b32 v[138:139], v11 offset0:32 offset1:36
	ds_read2_b32 v[140:141], v11 offset0:40 offset1:44
	ds_read2_b32 v[162:163], v11 offset0:48 offset1:52
	ds_read2_b32 v[168:169], v11 offset0:56 offset1:60
	ds_read2_b32 v[142:143], v11 offset0:64 offset1:68
	s_waitcnt lgkmcnt(8)
	v_lshlrev_b32_e32 v198, 16, v2
	v_and_b32_e32 v209, 0xffff0000, v2
	v_lshlrev_b32_e32 v205, 16, v3
	v_and_b32_e32 v204, 0xffff0000, v3
	ds_read2_b32 v[2:3], v11 offset0:72 offset1:76
	s_waitcnt lgkmcnt(1)
	v_lshlrev_b32_e32 v208, 16, v142
	v_and_b32_e32 v199, 0xffff0000, v142
	v_lshlrev_b32_e32 v171, 16, v143
	v_and_b32_e32 v170, 0xffff0000, v143
	s_waitcnt lgkmcnt(0)
	v_lshlrev_b32_e32 v155, 16, v2
	v_and_b32_e32 v154, 0xffff0000, v2
	v_lshlrev_b32_e32 v161, 16, v3
	v_and_b32_e32 v160, 0xffff0000, v3
	ds_read2_b32 v[2:3], v11 offset0:80 offset1:84
	v_lshlrev_b32_e32 v177, 16, v4
	v_and_b32_e32 v176, 0xffff0000, v4
	v_lshlrev_b32_e32 v149, 16, v162
	v_and_b32_e32 v148, 0xffff0000, v162
	s_waitcnt lgkmcnt(0)
	v_lshlrev_b32_e32 v181, 16, v2
	v_and_b32_e32 v180, 0xffff0000, v2
	v_lshlrev_b32_e32 v173, 16, v3
	v_and_b32_e32 v172, 0xffff0000, v3
	ds_read2_b32 v[2:3], v11 offset0:88 offset1:92
	v_lshlrev_b32_e32 v145, 16, v163
	v_and_b32_e32 v144, 0xffff0000, v163
	v_pk_add_f32 v[162:163], v[204:205], v[170:171] neg_lo:[0,1] neg_hi:[0,1]
	s_mov_b32 s6, s71
	s_waitcnt lgkmcnt(0)
	v_lshlrev_b32_e32 v165, 16, v2
	v_and_b32_e32 v164, 0xffff0000, v2
	v_lshlrev_b32_e32 v175, 16, v3
	v_and_b32_e32 v174, 0xffff0000, v3
	ds_read2_b32 v[2:3], v11 offset0:96 offset1:100
	s_mov_b32 s7, s70
	v_lshlrev_b32_e32 v191, 16, v6
	v_and_b32_e32 v190, 0xffff0000, v6
	v_lshlrev_b32_e32 v179, 16, v7
	s_waitcnt lgkmcnt(0)
	v_lshlrev_b32_e32 v206, 16, v2
	v_and_b32_e32 v202, 0xffff0000, v2
	v_lshlrev_b32_e32 v185, 16, v3
	v_and_b32_e32 v184, 0xffff0000, v3
	ds_read2_b32 v[2:3], v11 offset0:104 offset1:108
	v_and_b32_e32 v178, 0xffff0000, v7
	v_lshlrev_b32_e32 v183, 16, v8
	v_and_b32_e32 v182, 0xffff0000, v8
	v_lshlrev_b32_e32 v187, 16, v9
	s_waitcnt lgkmcnt(0)
	v_lshlrev_b32_e32 v157, 16, v2
	v_and_b32_e32 v156, 0xffff0000, v2
	v_lshlrev_b32_e32 v151, 16, v3
	v_and_b32_e32 v150, 0xffff0000, v3
	ds_read2_b32 v[2:3], v11 offset0:112 offset1:116
	v_and_b32_e32 v186, 0xffff0000, v9
	v_lshlrev_b32_e32 v203, 16, v138
	v_and_b32_e32 v207, 0xffff0000, v138
	v_lshlrev_b32_e32 v189, 16, v139
	s_waitcnt lgkmcnt(0)
	v_lshlrev_b32_e32 v147, 16, v2
	v_and_b32_e32 v146, 0xffff0000, v2
	v_lshlrev_b32_e32 v143, 16, v3
	v_and_b32_e32 v142, 0xffff0000, v3
	ds_read2_b32 v[2:3], v11 offset0:120 offset1:124
	v_and_b32_e32 v188, 0xffff0000, v139
	v_lshlrev_b32_e32 v159, 16, v140
	v_and_b32_e32 v158, 0xffff0000, v140
	v_lshlrev_b32_e32 v153, 16, v141
	v_and_b32_e32 v152, 0xffff0000, v141
	s_waitcnt lgkmcnt(0)
	v_lshlrev_b32_e32 v139, 16, v2
	v_lshlrev_b32_e32 v141, 16, v168
	v_and_b32_e32 v138, 0xffff0000, v2
	v_and_b32_e32 v140, 0xffff0000, v168
	v_lshlrev_b32_e32 v7, 16, v3
	v_lshlrev_b32_e32 v9, 16, v169
	v_and_b32_e32 v6, 0xffff0000, v3
	v_and_b32_e32 v8, 0xffff0000, v169
	v_pk_mul_f32 v[2:3], v[162:163], s[70:71]
	v_pk_mul_f32 v[162:163], v[162:163], s[6:7]
	v_pk_add_f32 v[168:169], v[176:177], v[154:155] neg_lo:[0,1] neg_hi:[0,1]
	s_mov_b32 s31, s66
	s_mov_b32 s67, s30
	v_lshlrev_b32_e32 v193, 16, v5
	v_and_b32_e32 v192, 0xffff0000, v5
	v_add_f32_e32 v3, v3, v2
	v_sub_f32_e32 v2, v162, v163
	v_add_f32_e32 v163, v155, v177
	v_add_f32_e32 v162, v154, v176
	v_pk_mul_f32 v[154:155], v[168:169], s[30:31]
	v_pk_mul_f32 v[168:169], v[168:169], s[66:67]
	v_add_f32_e32 v155, v155, v154
	v_sub_f32_e32 v154, v168, v169
	v_pk_add_f32 v[168:169], v[192:193], v[160:161] neg_lo:[0,1] neg_hi:[0,1]
	s_mov_b32 s4, s29
	s_mov_b32 s5, s28
	v_add_f32_e32 v177, v161, v193
	v_add_f32_e32 v176, v160, v192
	v_pk_mul_f32 v[160:161], v[168:169], s[28:29]
	v_pk_mul_f32 v[168:169], v[168:169], s[4:5]
	v_add_f32_e32 v161, v161, v160
	v_sub_f32_e32 v160, v168, v169
	v_pk_add_f32 v[168:169], v[190:191], v[180:181] neg_lo:[0,1] neg_hi:[0,1]
	v_add_f32_e32 v192, v181, v191
	v_pk_mul_f32 v[168:169], v[168:169], s[36:37] op_sel_hi:[1,0]
	v_add_f32_e32 v193, v180, v190
	v_add_f32_e32 v190, v169, v168
	v_sub_f32_e32 v191, v168, v169
	v_pk_add_f32 v[168:169], v[178:179], v[172:173] neg_lo:[0,1] neg_hi:[0,1]
	v_add_f32_e32 v5, v171, v205
	v_add_f32_e32 v4, v170, v204
	v_pk_mul_f32 v[170:171], v[168:169], s[4:5]
	v_pk_mul_f32 v[168:169], v[168:169], s[28:29]
	v_add_f32_e32 v180, v172, v178
	v_sub_f32_e32 v172, v168, v169
	v_pk_add_f32 v[168:169], v[182:183], v[164:165] neg_lo:[0,1] neg_hi:[0,1]
	v_add_f32_e32 v181, v173, v179
	v_add_f32_e32 v179, v165, v183
	v_add_f32_e32 v178, v164, v182
	v_pk_mul_f32 v[164:165], v[168:169], s[66:67]
	v_pk_mul_f32 v[168:169], v[168:169], s[30:31]
	v_add_f32_e32 v165, v165, v164
	v_sub_f32_e32 v164, v168, v169
	v_pk_add_f32 v[168:169], v[186:187], v[174:175] neg_lo:[0,1] neg_hi:[0,1]
	v_add_f32_e32 v173, v171, v170
	v_pk_mul_f32 v[170:171], v[168:169], s[6:7]
	v_pk_mul_f32 v[168:169], v[168:169], s[70:71]
	v_add_f32_e32 v183, v175, v187
	v_add_f32_e32 v182, v174, v186
	v_sub_f32_e32 v174, v168, v169
	v_sub_f32_e32 v168, v203, v206
	v_add_f32_e32 v187, v185, v189
	v_add_f32_e32 v186, v184, v188
	v_pk_add_f32 v[188:189], v[188:189], v[184:185] neg_lo:[0,1] neg_hi:[0,1]
	v_add_f32_e32 v204, v206, v203
	v_xor_b32_e32 v203, 0x80000000, v168
; template <int N, int LOGN> __device__ __forceinline__ void fft_dif(float (&re)[N], float (&im)[N]) {
; #pragma unroll
;     for (int st = 0; st < LOGN; ++st) { const int len = N >> st, half = len >> 1, step = 32 / len;
; #pragma unroll
;         for (int base = 0; base < N; base += len)
; #pragma unroll
;             for (int j = 0; j < half; ++j) { const int a = base + j, b = a + half;
;                 const float ar = re[a], ai = im[a], br = re[b], bi = im[b]; re[a] = ar + br; im[a] = ai + bi;
;                 const float dr = ar - br, di = ai - bi; const int m = (j * step) & 31;
;                 if (m == 0) { re[b] = dr; im[b] = di; }
;                 else if (m == 8) { re[b] = di; im[b] = -dr; }
;                 else { const float wr = C32[m], ws = C32[(m + 24) & 31]; re[b] = dr * wr + di * ws; im[b] = di * wr - dr * ws; }
;                 asm("" : "+v"(re[a])); asm("" : "+v"(im[a])); asm("" : "+v"(re[b])); asm("" : "+v"(im[b])); } }
	v_pk_mul_f32 v[168:169], v[188:189], s[6:7]
	s_mov_b32 s49, s71
	v_sub_f32_e32 v185, v168, v169
	v_pk_mul_f32 v[168:169], v[188:189], s[48:49]
	s_mov_b32 s27, s36
	v_sub_f32_e32 v184, v168, v169
	v_add_f32_e32 v168, v147, v149
	v_add_f32_e32 v169, v146, v148
	v_pk_add_f32 v[146:147], v[148:149], v[146:147] neg_lo:[0,1] neg_hi:[0,1]
	v_add_f32_e32 v175, v171, v170
	v_pk_mul_f32 v[148:149], v[146:147], s[26:27]
	v_add_f32_e32 v147, v143, v145
	v_fma_f32 v170, v146, s36, -v149
	v_add_f32_e32 v146, v142, v144
	v_pk_add_f32 v[144:145], v[144:145], v[142:143] neg_lo:[0,1] neg_hi:[0,1]
	s_mov_b32 s53, s28
	v_pk_mul_f32 v[142:143], v[144:145], s[28:29]
	v_pk_mul_f32 v[144:145], v[144:145], s[52:53]
	v_sub_f32_e32 v143, v142, v143
	v_sub_f32_e32 v142, v144, v145
	v_add_f32_e32 v145, v139, v141
	v_add_f32_e32 v144, v138, v140
	v_pk_add_f32 v[140:141], v[140:141], v[138:139] neg_lo:[0,1] neg_hi:[0,1]
	s_mov_b32 s47, s30
	v_pk_mul_f32 v[138:139], v[140:141], s[30:31]
	v_pk_mul_f32 v[140:141], v[140:141], s[46:47]
	v_sub_f32_e32 v139, v138, v139
	v_sub_f32_e32 v138, v140, v141
	v_add_f32_e32 v141, v7, v9
	v_add_f32_e32 v140, v6, v8
	v_pk_add_f32 v[6:7], v[8:9], v[6:7] neg_lo:[0,1] neg_hi:[0,1]
	s_mov_b32 s55, s70
	v_add_f32_e32 v189, v157, v159
	v_add_f32_e32 v188, v156, v158
	v_pk_add_f32 v[158:159], v[158:159], v[156:157] neg_lo:[0,1] neg_hi:[0,1]
	s_mov_b32 s69, s66
	v_pk_mul_f32 v[8:9], v[6:7], s[70:71]
	v_pk_mul_f32 v[6:7], v[6:7], s[54:55]
	v_pk_mul_f32 v[156:157], v[158:159], s[66:67]
	v_pk_mul_f32 v[158:159], v[158:159], s[68:69]
	v_sub_f32_e32 v9, v8, v9
	v_sub_f32_e32 v8, v6, v7
	v_add_f32_e32 v7, v5, v187
	v_add_f32_e32 v6, v4, v186
	v_pk_add_f32 v[4:5], v[4:5], v[186:187] neg_lo:[0,1] neg_hi:[0,1]
	v_sub_f32_e32 v157, v156, v157
	v_sub_f32_e32 v156, v158, v159
	v_add_f32_e32 v159, v151, v153
	v_add_f32_e32 v158, v150, v152
	v_pk_add_f32 v[152:153], v[152:153], v[150:151] neg_lo:[0,1] neg_hi:[0,1]
	s_mov_b32 s51, s29
	v_sub_f32_e32 v171, v148, v149
	v_pk_mul_f32 v[148:149], v[4:5], s[30:31]
	v_pk_mul_f32 v[4:5], v[4:5], s[66:67]
	v_pk_mul_f32 v[150:151], v[152:153], s[4:5]
	v_pk_mul_f32 v[152:153], v[152:153], s[50:51]
	v_add_f32_e32 v149, v149, v148
	v_sub_f32_e32 v148, v4, v5
	v_pk_add_f32 v[4:5], v[162:163], v[188:189] neg_lo:[0,1] neg_hi:[0,1]
	v_sub_f32_e32 v151, v150, v151
	v_sub_f32_e32 v150, v152, v153
	v_pk_mul_f32 v[4:5], v[4:5], s[36:37] op_sel_hi:[1,0]
	v_pk_add_f32 v[152:153], v[176:177], v[158:159] neg_lo:[0,1] neg_hi:[0,1]
	v_add_f32_e32 v186, v163, v189
	v_add_f32_e32 v187, v162, v188
	v_add_f32_e32 v188, v5, v4
	v_sub_f32_e32 v189, v4, v5
	v_add_f32_e32 v5, v177, v159
	v_add_f32_e32 v4, v176, v158
	v_pk_mul_f32 v[158:159], v[152:153], s[66:67]
	v_pk_mul_f32 v[152:153], v[152:153], s[30:31]
	v_add_f32_e32 v159, v159, v158
	v_sub_f32_e32 v158, v152, v153
	v_sub_f32_e32 v152, v192, v168
	v_add_f32_e32 v176, v192, v168
	v_xor_b32_e32 v192, 0x80000000, v152
	v_add_f32_e32 v153, v181, v147
	v_add_f32_e32 v152, v180, v146
	v_pk_add_f32 v[146:147], v[180:181], v[146:147] neg_lo:[0,1] neg_hi:[0,1]
	s_nop 0
	v_pk_mul_f32 v[162:163], v[146:147], s[66:67]
	v_pk_mul_f32 v[146:147], v[146:147], s[68:69]
	v_add_f32_e32 v180, v179, v145
	v_add_f32_e32 v181, v178, v144
	v_pk_add_f32 v[144:145], v[178:179], v[144:145] neg_lo:[0,1] neg_hi:[0,1]
	v_sub_f32_e32 v163, v162, v163
	v_sub_f32_e32 v162, v146, v147
	v_pk_mul_f32 v[146:147], v[144:145], s[26:27]
	v_add_f32_e32 v145, v183, v141
	v_fma_f32 v178, v144, s36, -v147
	v_add_f32_e32 v144, v182, v140
	v_pk_add_f32 v[140:141], v[182:183], v[140:141] neg_lo:[0,1] neg_hi:[0,1]
	v_sub_f32_e32 v179, v146, v147
	v_pk_mul_f32 v[146:147], v[140:141], s[30:31]
	v_pk_mul_f32 v[140:141], v[140:141], s[46:47]
	v_sub_f32_e32 v147, v146, v147
	v_sub_f32_e32 v146, v140, v141
	v_add_f32_e32 v141, v3, v185
	v_add_f32_e32 v140, v2, v184
	v_pk_add_f32 v[2:3], v[2:3], v[184:185] neg_lo:[0,1] neg_hi:[0,1]
	v_add_f32_e32 v177, v193, v169
	v_sub_f32_e32 v193, v193, v169
	v_pk_mul_f32 v[168:169], v[2:3], s[30:31]
	v_pk_mul_f32 v[2:3], v[2:3], s[66:67]
	v_add_f32_e32 v200, v208, v198
	v_add_f32_e32 v201, v199, v209
	v_sub_f32_e32 v199, v209, v199
	v_sub_f32_e32 v198, v198, v208
	v_add_f32_e32 v205, v202, v207
	v_sub_f32_e32 v202, v207, v202
	v_add_f32_e32 v169, v169, v168
	v_sub_f32_e32 v168, v2, v3
	v_pk_add_f32 v[2:3], v[154:155], v[156:157] neg_lo:[0,1] neg_hi:[0,1]
	s_nop 0
	v_pk_mul_f32 v[2:3], v[2:3], s[36:37] op_sel_hi:[1,0]
	v_add_f32_e32 v182, v198, v202
	v_add_f32_e32 v183, v199, v203
	v_sub_f32_e32 v199, v199, v203
	v_sub_f32_e32 v198, v198, v202
	v_add_f32_e32 v202, v3, v2
	v_sub_f32_e32 v203, v2, v3
	v_add_f32_e32 v3, v161, v151
	v_add_f32_e32 v2, v160, v150
	v_pk_add_f32 v[150:151], v[160:161], v[150:151] neg_lo:[0,1] neg_hi:[0,1]
	v_add_f32_e32 v184, v155, v157
	v_add_f32_e32 v185, v154, v156
	v_pk_mul_f32 v[154:155], v[150:151], s[66:67]
	v_pk_mul_f32 v[150:151], v[150:151], s[30:31]
	v_add_f32_e32 v155, v155, v154
	v_sub_f32_e32 v154, v150, v151
	v_sub_f32_e32 v150, v190, v170
	v_add_f32_e32 v160, v190, v170
	v_xor_b32_e32 v170, 0x80000000, v150
	v_add_f32_e32 v151, v173, v143
	v_add_f32_e32 v150, v172, v142
	v_pk_add_f32 v[142:143], v[172:173], v[142:143] neg_lo:[0,1] neg_hi:[0,1]
	s_nop 0
	v_pk_mul_f32 v[156:157], v[142:143], s[66:67]
	v_pk_mul_f32 v[142:143], v[142:143], s[68:69]
	v_add_f32_e32 v172, v165, v139
	v_add_f32_e32 v173, v164, v138
	v_pk_add_f32 v[138:139], v[164:165], v[138:139] neg_lo:[0,1] neg_hi:[0,1]
	v_sub_f32_e32 v157, v156, v157
	v_sub_f32_e32 v156, v142, v143
	v_pk_mul_f32 v[142:143], v[138:139], s[26:27]
	v_add_f32_e32 v139, v175, v9
	v_fma_f32 v164, v138, s36, -v143
; template <int N, int LOGN> __device__ __forceinline__ void fft_dif(float (&re)[N], float (&im)[N]) {
; #pragma unroll
;     for (int st = 0; st < LOGN; ++st) { const int len = N >> st, half = len >> 1, step = 32 / len;
; #pragma unroll
;         for (int base = 0; base < N; base += len)
; #pragma unroll
;             for (int j = 0; j < half; ++j) { const int a = base + j, b = a + half;
;                 const float ar = re[a], ai = im[a], br = re[b], bi = im[b]; re[a] = ar + br; im[a] = ai + bi;
;                 const float dr = ar - br, di = ai - bi; const int m = (j * step) & 31;
;                 if (m == 0) { re[b] = dr; im[b] = di; }
;                 else if (m == 8) { re[b] = di; im[b] = -dr; }
;                 else { const float wr = C32[m], ws = C32[(m + 24) & 31]; re[b] = dr * wr + di * ws; im[b] = di * wr - dr * ws; }
;                 asm("" : "+v"(re[a])); asm("" : "+v"(im[a])); asm("" : "+v"(re[b])); asm("" : "+v"(im[b])); } }
	v_add_f32_e32 v138, v174, v8
	v_pk_add_f32 v[8:9], v[174:175], v[8:9] neg_lo:[0,1] neg_hi:[0,1]
	s_nop 0
	v_add_f32_e32 v206, v200, v204
	v_add_f32_e32 v207, v201, v205
	v_sub_f32_e32 v165, v142, v143
	v_pk_mul_f32 v[142:143], v[8:9], s[30:31]
	v_pk_mul_f32 v[8:9], v[8:9], s[46:47]
	v_sub_f32_e32 v143, v142, v143
	v_sub_f32_e32 v142, v8, v9
	v_add_f32_e32 v8, v206, v176
	v_add_f32_e32 v9, v207, v177
	v_sub_f32_e32 v174, v207, v177
	v_sub_f32_e32 v175, v206, v176
	v_add_f32_e32 v176, v7, v153
	v_add_f32_e32 v177, v6, v152
	v_pk_add_f32 v[6:7], v[6:7], v[152:153] neg_lo:[0,1] neg_hi:[0,1]
	s_nop 0
	v_pk_mul_f32 v[6:7], v[6:7], s[36:37] op_sel_hi:[1,0]
	v_add_f32_e32 v161, v191, v171
	v_sub_f32_e32 v171, v191, v171
	v_add_f32_e32 v152, v7, v6
	v_sub_f32_e32 v153, v6, v7
	v_add_f32_e32 v190, v186, v180
	v_add_f32_e32 v191, v187, v181
	v_sub_f32_e32 v181, v187, v181
	v_sub_f32_e32 v6, v186, v180
	v_add_f32_e32 v186, v5, v145
	v_add_f32_e32 v187, v4, v144
	v_pk_add_f32 v[4:5], v[4:5], v[144:145] neg_lo:[0,1] neg_hi:[0,1]
	v_xor_b32_e32 v180, 0x80000000, v6
	v_pk_mul_f32 v[6:7], v[4:5], s[26:27]
	v_sub_f32_e32 v201, v201, v205
	v_sub_f32_e32 v200, v200, v204
	v_fma_f32 v144, v4, s36, -v7
	v_pk_add_f32 v[4:5], v[148:149], v[162:163] neg_lo:[0,1] neg_hi:[0,1]
	s_nop 0
	v_pk_mul_f32 v[4:5], v[4:5], s[36:37] op_sel_hi:[1,0]
	v_add_f32_e32 v204, v200, v193
	v_add_f32_e32 v205, v201, v192
	v_sub_f32_e32 v192, v201, v192
	v_sub_f32_e32 v193, v200, v193
	v_add_f32_e32 v200, v149, v163
	v_add_f32_e32 v201, v148, v162
	v_add_f32_e32 v148, v5, v4
	v_sub_f32_e32 v149, v4, v5
	v_sub_f32_e32 v4, v188, v178
	v_add_f32_e32 v162, v188, v178
	v_xor_b32_e32 v178, 0x80000000, v4
	v_pk_add_f32 v[4:5], v[158:159], v[146:147] neg_lo:[0,1] neg_hi:[0,1]
	v_sub_f32_e32 v145, v6, v7
	v_pk_mul_f32 v[6:7], v[4:5], s[26:27]
	v_add_f32_e32 v163, v189, v179
	v_sub_f32_e32 v179, v189, v179
	v_add_f32_e32 v189, v158, v146
	v_fma_f32 v146, v4, s36, -v7
	v_pk_add_f32 v[4:5], v[140:141], v[150:151] neg_lo:[0,1] neg_hi:[0,1]
	s_nop 0
	v_pk_mul_f32 v[4:5], v[4:5], s[36:37] op_sel_hi:[1,0]
	v_add_f32_e32 v188, v159, v147
	v_sub_f32_e32 v6, v6, v7
	v_add_f32_e32 v7, v182, v160
	v_add_f32_e32 v147, v183, v161
	v_sub_f32_e32 v158, v183, v161
	v_sub_f32_e32 v159, v182, v160
	v_add_f32_e32 v160, v141, v151
	v_add_f32_e32 v161, v140, v150
	v_add_f32_e32 v140, v5, v4
	v_sub_f32_e32 v141, v4, v5
	v_sub_f32_e32 v4, v184, v172
	v_add_f32_e32 v182, v3, v139
	v_add_f32_e32 v183, v2, v138
	v_pk_add_f32 v[2:3], v[2:3], v[138:139] neg_lo:[0,1] neg_hi:[0,1]
	v_add_f32_e32 v150, v184, v172
	v_xor_b32_e32 v172, 0x80000000, v4
	v_pk_mul_f32 v[4:5], v[2:3], s[26:27]
	s_nop 0
	v_fma_f32 v138, v2, s36, -v5
	v_pk_add_f32 v[2:3], v[168:169], v[156:157] neg_lo:[0,1] neg_hi:[0,1]
	s_nop 0
	v_pk_mul_f32 v[2:3], v[2:3], s[36:37] op_sel_hi:[1,0]
	v_add_f32_e32 v151, v185, v173
	v_sub_f32_e32 v173, v185, v173
	v_add_f32_e32 v184, v198, v171
	v_add_f32_e32 v185, v199, v170
	v_sub_f32_e32 v170, v199, v170
	v_sub_f32_e32 v171, v198, v171
	v_add_f32_e32 v198, v169, v157
	v_add_f32_e32 v199, v168, v156
	v_add_f32_e32 v156, v3, v2
	v_sub_f32_e32 v157, v2, v3
	v_sub_f32_e32 v2, v202, v164
	v_add_f32_e32 v168, v202, v164
	v_xor_b32_e32 v164, 0x80000000, v2
	v_pk_add_f32 v[2:3], v[154:155], v[142:143] neg_lo:[0,1] neg_hi:[0,1]
	v_sub_f32_e32 v139, v4, v5
	v_pk_mul_f32 v[4:5], v[2:3], s[26:27]
	v_add_f32_e32 v169, v203, v165
	v_sub_f32_e32 v165, v203, v165
	v_add_f32_e32 v202, v155, v143
	v_add_f32_e32 v203, v154, v142
	v_fma_f32 v2, v2, s36, -v5
	v_sub_f32_e32 v3, v4, v5
	v_add_f32_e32 v4, v8, v190
	v_add_f32_e32 v5, v9, v191
	v_sub_f32_e32 v9, v9, v191
	v_add_f32_e32 v142, v176, v186
	v_add_f32_e32 v143, v177, v187
	v_sub_f32_e32 v154, v177, v187
	v_sub_f32_e32 v155, v176, v186
	v_add_f32_e32 v177, v174, v180
	v_sub_f32_e32 v174, v174, v180
	v_add_f32_e32 v180, v152, v144
	v_sub_f32_e32 v144, v152, v144
	v_add_f32_e32 v186, v200, v188
	v_sub_f32_e32 v188, v200, v188
	v_add_f32_e32 v191, v192, v178
	v_sub_f32_e32 v178, v192, v178
	v_add_f32_e32 v192, v148, v146
	v_sub_f32_e32 v146, v148, v146
	v_sub_f32_e32 v8, v8, v190
	v_xor_b32_e32 v155, 0x80000000, v155
	v_add_f32_e32 v176, v175, v181
	v_sub_f32_e32 v175, v175, v181
	v_add_f32_e32 v181, v153, v145
	v_sub_f32_e32 v145, v153, v145
	v_xor_b32_e32 v144, 0x80000000, v144
	v_add_f32_e32 v152, v204, v162
	v_add_f32_e32 v153, v205, v163
	v_sub_f32_e32 v163, v205, v163
	v_sub_f32_e32 v162, v204, v162
	v_add_f32_e32 v187, v201, v189
	v_sub_f32_e32 v189, v201, v189
	v_xor_b32_e32 v188, 0x80000000, v188
	v_add_f32_e32 v190, v193, v179
	v_sub_f32_e32 v179, v193, v179
	v_add_f32_e32 v193, v149, v6
	v_sub_f32_e32 v6, v149, v6
	v_xor_b32_e32 v146, 0x80000000, v146
	v_add_f32_e32 v148, v7, v150
	v_add_f32_e32 v149, v147, v151
	v_sub_f32_e32 v147, v147, v151
	v_sub_f32_e32 v7, v7, v150
	v_add_f32_e32 v150, v160, v182
	v_add_f32_e32 v151, v161, v183
	v_sub_f32_e32 v161, v161, v183
	v_sub_f32_e32 v160, v160, v182
	v_add_f32_e32 v183, v158, v172
	v_sub_f32_e32 v158, v158, v172
	v_add_f32_e32 v172, v140, v138
	v_sub_f32_e32 v138, v140, v138
	v_xor_b32_e32 v160, 0x80000000, v160
	v_add_f32_e32 v182, v159, v173
	v_sub_f32_e32 v159, v159, v173
	v_add_f32_e32 v173, v141, v139
	v_sub_f32_e32 v139, v141, v139
	v_xor_b32_e32 v138, 0x80000000, v138
	v_add_f32_e32 v140, v184, v168
	v_add_f32_e32 v141, v185, v169
	v_add_f32_e32 v200, v171, v165
; __device__ __forceinline__ unsigned cvt_pk_bf16(float lo, float hi) { f32x2_t v = {lo, hi}; bf16x2_t b = __builtin_convertvector(v, bf16x2_t); return __builtin_bit_cast(unsigned, b); }
; #define LAS __attribute__((address_space(3)))
; __device__ __forceinline__ void fft_phase(Frame& F, const bf16* Yc, bf16* Y) {
;     ...
;               fft_dif<32, 5>(re, im);
; #pragma unroll
;               for (int k = 0; k < 32; ++k) *(LAS unsigned*)(l3 + 4 * c + 16 * k) = pg8::cvt_pk_bf16(re[BR5[k]], im[BR5[k]]); } }
;         __syncthreads();
;         bf16* dst = Y + ((size_t)b * SEQ) * 1024 + 128 * g;
;         const float sc1 = 1.0f / 1024.0f;
; #pragma unroll 2
;         for (int i = 0; i < 16; ++i) { const int k = t + 512 * i, km = (SEQ - k) & (SEQ - 1);
	v_add_f32_e32 v201, v170, v164
	v_sub_f32_e32 v164, v170, v164
	v_sub_f32_e32 v165, v171, v165
	v_add_f32_e32 v170, v156, v2
	v_add_f32_e32 v171, v157, v3
	v_sub_f32_e32 v3, v157, v3
	v_sub_f32_e32 v2, v156, v2
	v_add_f32_e32 v156, v4, v142
	v_add_f32_e32 v157, v5, v143
	v_sub_f32_e32 v5, v5, v143
	v_sub_f32_e32 v4, v4, v142
	v_sub_f32_e32 v169, v185, v169
	v_sub_f32_e32 v168, v184, v168
	v_add_f32_e32 v184, v198, v202
	v_add_f32_e32 v185, v199, v203
	v_sub_f32_e32 v198, v198, v202
	v_add_f32_e32 v142, v8, v154
	v_add_f32_e32 v143, v9, v155
	v_sub_f32_e32 v9, v9, v155
	v_sub_f32_e32 v8, v8, v154
	v_add_f32_e32 v154, v176, v180
	v_add_f32_e32 v155, v177, v181
	v_sub_f32_e32 v177, v177, v181
	v_sub_f32_e32 v176, v176, v180
	v_add_f32_e32 v180, v175, v145
	v_add_f32_e32 v181, v174, v144
	v_sub_f32_e32 v144, v174, v144
	v_sub_f32_e32 v145, v175, v145
	v_add_f32_e32 v174, v152, v186
	v_add_f32_e32 v175, v153, v187
	v_sub_f32_e32 v153, v153, v187
	v_sub_f32_e32 v152, v152, v186
	v_add_f32_e32 v186, v162, v189
	v_add_f32_e32 v187, v163, v188
	v_sub_f32_e32 v163, v163, v188
	v_sub_f32_e32 v162, v162, v189
	v_add_f32_e32 v188, v190, v192
	v_add_f32_e32 v189, v191, v193
	v_sub_f32_e32 v191, v191, v193
	v_sub_f32_e32 v190, v190, v192
	v_add_f32_e32 v192, v179, v6
	v_add_f32_e32 v193, v178, v146
	v_sub_f32_e32 v146, v178, v146
	v_sub_f32_e32 v6, v179, v6
	v_add_f32_e32 v178, v148, v150
	v_add_f32_e32 v179, v149, v151
	v_sub_f32_e32 v149, v149, v151
	v_sub_f32_e32 v148, v148, v150
	v_sub_f32_e32 v199, v199, v203
	v_xor_b32_e32 v198, 0x80000000, v198
	v_add_f32_e32 v150, v7, v161
	v_add_f32_e32 v151, v147, v160
	v_sub_f32_e32 v147, v147, v160
	v_sub_f32_e32 v7, v7, v161
	v_add_f32_e32 v160, v182, v172
	v_add_f32_e32 v161, v183, v173
	v_sub_f32_e32 v173, v183, v173
	v_sub_f32_e32 v172, v182, v172
	v_add_f32_e32 v182, v159, v139
	v_add_f32_e32 v183, v158, v138
	v_sub_f32_e32 v138, v158, v138
	v_sub_f32_e32 v139, v159, v139
	v_add_f32_e32 v158, v140, v184
	v_add_f32_e32 v159, v141, v185
	v_sub_f32_e32 v141, v141, v185
	v_sub_f32_e32 v140, v140, v184
	v_cvt_pk_bf16_f32 v4, v4, v5
	v_cvt_pk_bf16_f32 v5, v148, v149
	ds_write2_b32 v11, v4, v5 offset0:64 offset1:68
	v_cvt_pk_bf16_f32 v4, v152, v153
	v_cvt_pk_bf16_f32 v5, v140, v141
	v_add_f32_e32 v184, v168, v199
	v_add_f32_e32 v185, v169, v198
	v_sub_f32_e32 v169, v169, v198
	v_sub_f32_e32 v168, v168, v199
	v_add_f32_e32 v198, v200, v170
	v_add_f32_e32 v199, v201, v171
	v_sub_f32_e32 v171, v201, v171
	v_sub_f32_e32 v170, v200, v170
	ds_write2_b32 v11, v4, v5 offset0:72 offset1:76
	v_cvt_pk_bf16_f32 v4, v176, v177
	v_cvt_pk_bf16_f32 v5, v172, v173
	v_xor_b32_e32 v2, 0x80000000, v2
	ds_write2_b32 v11, v4, v5 offset0:80 offset1:84
	v_cvt_pk_bf16_f32 v4, v190, v191
	v_cvt_pk_bf16_f32 v5, v170, v171
	v_cvt_pk_bf16_f32 v142, v142, v143
	v_cvt_pk_bf16_f32 v143, v150, v151
	ds_write2_b32 v11, v4, v5 offset0:88 offset1:92
	v_cvt_pk_bf16_f32 v4, v8, v9
	v_cvt_pk_bf16_f32 v5, v7, v147
	s_nop 0
	v_add_f32_e32 v201, v164, v2
	v_sub_f32_e32 v2, v164, v2
	ds_write2_b32 v11, v142, v143 offset0:32 offset1:36
	v_cvt_pk_bf16_f32 v142, v186, v187
	v_cvt_pk_bf16_f32 v143, v184, v185
	ds_write2_b32 v11, v4, v5 offset0:96 offset1:100
	v_cvt_pk_bf16_f32 v4, v162, v163
	v_cvt_pk_bf16_f32 v5, v168, v169
	s_nop 0
	v_add_f32_e32 v200, v165, v3
	v_sub_f32_e32 v3, v165, v3
	v_cvt_pk_bf16_f32 v156, v156, v157
	v_cvt_pk_bf16_f32 v157, v178, v179
	v_cvt_pk_bf16_f32 v154, v154, v155
	v_cvt_pk_bf16_f32 v155, v160, v161
	ds_write2_b32 v11, v142, v143 offset0:40 offset1:44
	v_cvt_pk_bf16_f32 v142, v180, v181
	v_cvt_pk_bf16_f32 v143, v182, v183
	ds_write2_b32 v11, v4, v5 offset0:104 offset1:108
	v_cvt_pk_bf16_f32 v4, v145, v144
	v_cvt_pk_bf16_f32 v5, v139, v138
	ds_write2_b32 v11, v156, v157 offset1:4
	v_cvt_pk_bf16_f32 v156, v174, v175
	v_cvt_pk_bf16_f32 v157, v158, v159
	ds_write2_b32 v11, v154, v155 offset0:16 offset1:20
	v_cvt_pk_bf16_f32 v154, v188, v189
	v_cvt_pk_bf16_f32 v155, v198, v199
	ds_write2_b32 v11, v142, v143 offset0:48 offset1:52
	v_cvt_pk_bf16_f32 v142, v192, v193
	v_cvt_pk_bf16_f32 v143, v200, v201
	ds_write2_b32 v11, v4, v5 offset0:112 offset1:116
	v_cvt_pk_bf16_f32 v4, v6, v146
	v_cvt_pk_bf16_f32 v2, v3, v2
	s_mov_b32 s0, 4
	s_mov_b64 s[4:5], 0
	s_and_b64 vcc, exec, vcc
	ds_write2_b32 v11, v156, v157 offset0:8 offset1:12
	ds_write2_b32 v11, v154, v155 offset0:24 offset1:28
	ds_write2_b32 v11, v142, v143 offset0:56 offset1:60
	ds_write2_b32 v11, v4, v2 offset0:120 offset1:124
	s_cbranch_vccz .LBB0_201
	s_and_b32 s2, s16, 15
	s_lshl_b32 s18, s2, 3
	s_ashr_i32 s2, s17, 7
	s_and_b32 s0, s9, 7
	s_ashr_i32 s3, s2, 31
	s_lshl_b32 s0, s0, 8
	s_lshl_b64 s[2:3], s[2:3], 24
	s_add_u32 s4, s74, s2
	s_addc_u32 s5, s75, s3
	s_lshl_b32 s6, s8, 8
	s_add_u32 s4, s4, s6
	s_addc_u32 s5, s5, 0
	s_cmp_eq_u32 s10, 0
	s_cselect_b64 s[6:7], -1, 0
	s_cmp_lg_u32 s10, 0
	s_cselect_b64 s[8:9], -1, 0
	s_lshl_b32 s19, s10, 2
	s_sub_u32 s12, 0, s19
	s_subb_u32 s13, 0, 0
	s_or_b32 s2, s2, s0
	s_sub_u32 s14, s2, s18
	s_subb_u32 s15, s3, 0
	v_lshl_add_u64 v[138:139], v[134:135], 0, s[14:15]
	s_lshl_b32 s14, s18, 1
	s_or_b32 s14, s2, s14
	s_mov_b32 s15, s3
	s_mov_b64 s[10:11], 0
	v_lshl_add_u64 v[140:141], v[136:137], 0, s[14:15]
	v_lshl_add_u64 v[142:143], v[134:135], 0, s[2:3]
	s_lshl_b32 s0, s19, 2
	v_mov_b32_e32 v11, v197
	v_mov_b32_e32 v148, v10
	s_mov_b32 s18, 0x5040100
	s_waitcnt lgkmcnt(0)
	s_barrier
	s_branch .LBB0_204

; __device__ __forceinline__ unsigned cvt_pk_bf16(float lo, float hi) { f32x2_t v = {lo, hi}; bf16x2_t b = __builtin_convertvector(v, bf16x2_t); return __builtin_bit_cast(unsigned, b); }
; #define GAS __attribute__((address_space(1)))
; #define LAS __attribute__((address_space(3)))
; __device__ __forceinline__ void fft_phase(Frame& F, const bf16* Yc, bf16* Y) {
;     ...
;         for (int i = 0; i < 16; ++i) { const int k = t + 512 * i, km = (SEQ - k) & (SEQ - 1);
;             const v4u v = *(const LAS v4u*)(buf + fft_slot(k)), w = *(const LAS v4u*)(buf + fft_slot(km));
;             float d0 = bflo(v.x) * sc1, m0 = bflo(w.x) * sc1;
;             if (q4 == 0) { d0 = 0.5f * sc1 * (bflo(v.x) + bflo(w.x)); m0 = 0.5f * sc1 * (bfhi(v.x) + bfhi(w.x)); }
;             bf16* row = dst + (size_t)k * 1024;
;             v2u o; o.x = pg8::cvt_pk_bf16(d0, bflo(v.y) * sc1); o.y = pg8::cvt_pk_bf16(bflo(v.z) * sc1, bflo(v.w) * sc1);
;             *(GAS v2u*)(row + 4 * q4) = o;
;             const unsigned m12 = pg8::cvt_pk_bf16(bflo(w.z) * sc1, bflo(w.y) * sc1);
;             const unsigned m3 = pg8::cvt_pk_bf16(bflo(w.w) * sc1, 0.f) & 0xffffu, mz = pg8::cvt_pk_bf16(m0, 0.f) & 0xffffu;
;             if (q4 != 0) { P8u o2; o2.a = m3 | (m12 << 16); o2.b = (m12 >> 16) | (mz << 16); *(P8u*)(row + 125 - 4 * q4) = o2; }
;             else { row[125] = (bf16)m3; *(GAS unsigned*)(row + 126) = m12; row[64] = (bf16)mz; }
.LBB0_207:
	v_lshlrev_b32_e32 v2, 16, v7
	v_lshlrev_b32_e32 v9, 16, v9
	v_lshlrev_b32_e32 v8, 16, v8
	v_mul_f32_e32 v2, 0x3a800000, v2
	v_pk_mul_f32 v[8:9], v[8:9], s[64:65] op_sel_hi:[1,0]
	v_cvt_pk_bf16_f32 v6, v144, v2
	v_cvt_pk_bf16_f32 v7, v8, v9
	v_lshlrev_b32_e32 v147, 16, v4
	v_lshlrev_b32_e32 v146, 16, v3
	v_pk_mul_f32 v[2:3], v[146:147], s[64:65] op_sel_hi:[1,0]
	s_nop 0
	v_pk_mov_b32 v[2:3], v[2:3], v[2:3] op_sel:[1,0]
	v_cvt_pk_bf16_f32 v3, v2, v3
	v_lshlrev_b32_e32 v2, 16, v5
	v_mul_f32_e32 v2, 0x3a800000, v2
	v_cvt_pk_bf16_f32 v4, v2, 0
	v_cvt_pk_bf16_f32 v2, v145, 0
	v_and_b32_e32 v5, 0xffff, v4
	v_lshl_or_b32 v8, v3, 16, v5
	v_alignbit_b32 v9, v2, v3, 16
	v_lshl_add_u64 v[152:153], v[140:141], 0, s[10:11]
	global_store_dwordx4 v[152:153], v[6:9], off

; __device__ __forceinline__ unsigned cvt_pk_bf16(float lo, float hi) { f32x2_t v = {lo, hi}; bf16x2_t b = __builtin_convertvector(v, bf16x2_t); return __builtin_bit_cast(unsigned, b); }
; #define GAS __attribute__((address_space(1)))
; #define LAS __attribute__((address_space(3)))
; __device__ __forceinline__ void fft_phase(Frame& F, const bf16* Yc, bf16* Y) {
;     ...
;         for (int i = 0; i < 16; ++i) { const int k = t + 512 * i, km = (SEQ - k) & (SEQ - 1);
;             const v4u v = *(const LAS v4u*)(buf + fft_slot(k)), w = *(const LAS v4u*)(buf + fft_slot(km));
;             float d0 = bflo(v.x) * sc1, m0 = bflo(w.x) * sc1;
;             if (q4 == 0) { d0 = 0.5f * sc1 * (bflo(v.x) + bflo(w.x)); m0 = 0.5f * sc1 * (bfhi(v.x) + bfhi(w.x)); }
;             bf16* row = dst + (size_t)k * 1024;
;             v2u o; o.x = pg8::cvt_pk_bf16(d0, bflo(v.y) * sc1); o.y = pg8::cvt_pk_bf16(bflo(v.z) * sc1, bflo(v.w) * sc1);
;             *(GAS v2u*)(row + 4 * q4) = o;
;             const unsigned m12 = pg8::cvt_pk_bf16(bflo(w.z) * sc1, bflo(w.y) * sc1);
;             const unsigned m3 = pg8::cvt_pk_bf16(bflo(w.w) * sc1, 0.f) & 0xffffu, mz = pg8::cvt_pk_bf16(m0, 0.f) & 0xffffu;
;             if (q4 != 0) { P8u o2; o2.a = m3 | (m12 << 16); o2.b = (m12 >> 16) | (mz << 16); *(P8u*)(row + 125 - 4 * q4) = o2; }
;             else { row[125] = (bf16)m3; *(GAS unsigned*)(row + 126) = m12; row[64] = (bf16)mz; }
.LBB0_214:
	v_ashrrev_i32_e32 v145, 31, v144
	v_lshlrev_b64 v[144:145], 11, v[144:145]
	v_lshlrev_b32_e32 v2, 16, v7
	v_lshlrev_b32_e32 v9, 16, v9
	v_lshlrev_b32_e32 v8, 16, v8
	v_lshl_add_u64 v[144:145], s[4:5], 0, v[144:145]
	v_mul_f32_e32 v2, 0x3a800000, v2
	v_pk_mul_f32 v[8:9], v[8:9], s[64:65] op_sel_hi:[1,0]
	v_cvt_pk_bf16_f32 v6, v146, v2
	v_cvt_pk_bf16_f32 v7, v8, v9
	v_lshlrev_b32_e32 v151, 16, v4
	v_lshlrev_b32_e32 v150, 16, v3
	v_pk_mul_f32 v[2:3], v[150:151], s[64:65] op_sel_hi:[1,0]
	s_nop 0
	v_pk_mov_b32 v[2:3], v[2:3], v[2:3] op_sel:[1,0]
	v_cvt_pk_bf16_f32 v2, v2, v3
	v_lshlrev_b32_e32 v3, 16, v5
	v_mul_f32_e32 v3, 0x3a800000, v3
	v_cvt_pk_bf16_f32 v4, v3, 0
	v_cvt_pk_bf16_f32 v3, v147, 0
	v_and_b32_e32 v5, 0xffff, v4
	v_lshl_or_b32 v8, v2, 16, v5
	v_alignbit_b32 v9, v3, v2, 16
	v_lshl_add_u64 v[150:151], v[144:145], 0, s[0:1]
	global_store_dwordx4 v[150:151], v[6:9], off
	s_branch .LBB0_203

; __device__ __forceinline__ unsigned xb_ld(unsigned* p)              { return __hip_atomic_load(p, __ATOMIC_RELAXED, __HIP_MEMORY_SCOPE_AGENT); }
; __device__ __forceinline__ unsigned xb_add(unsigned* p, unsigned v) { return __hip_atomic_fetch_add(p, v, __ATOMIC_RELAXED, __HIP_MEMORY_SCOPE_AGENT); }
; #define XB_SPIN(cond, bar) do { unsigned _sp = 0; while (cond) { __builtin_amdgcn_s_sleep(1); \
;     if ((++_sp & 255u) == 0u) { if (xb_ld(&(bar)[XB_TMO])) break; if (_sp > XB_SPIN_CAP) { atomicAdd(&(bar)[XB_TMO], 1u); break; } } } } while (0)
; #define SEAM(k) do { if (!MK_PER_PHASE && IN(k) && IN((k) + 1)) xcd_barrier(bar); } while (0)
; __device__ __forceinline__ void xcd_barrier(const XcdBarrier& b) {
;     asm volatile("s_waitcnt vmcnt(0)" ::: "memory");
;     __syncthreads();
;     if (threadIdx.x == 0) {
;         unsigned* bar = b.bar;
;         __builtin_amdgcn_s_waitcnt(0);
;         unsigned nloc = b.st[0], nx = b.st[1];
;         if (nloc == 0u) { xcd_barrier_complete(bar, b.x, nloc, nx); b.st[0] = nloc; b.st[1] = nx; }
;         const unsigned old = xb_add(&bar[XB_XSUB(b.x)], 1u);
;         const unsigned gen = old / nloc;
;         if (old + 1u == (gen + 1u) * nloc) {
;             __builtin_amdgcn_fence(__ATOMIC_RELEASE, "agent");
;             asm volatile("s_waitcnt vmcnt(0)" ::: "memory");
;             const unsigned og = xb_add(&bar[XB_TOP], 1u);
;             const unsigned tg = og / nx;
;             if (og + 1u == (tg + 1u) * nx) xb_add(&bar[XB_TOPGEN], 1u);
;             else XB_SPIN(xb_ld(&bar[XB_TOPGEN]) == tg, bar);
;             __builtin_amdgcn_fence(__ATOMIC_ACQUIRE, "agent");
;             xb_add(&bar[XB_XGEN(b.x)], 1u);
;             asm volatile("s_waitcnt vmcnt(0)" ::: "memory");
;         } else {
;             XB_SPIN(xb_ld(&bar[XB_XGEN(b.x)]) == gen, bar);
;             __builtin_amdgcn_fence(__ATOMIC_ACQUIRE, "agent");
;             asm volatile("s_waitcnt vmcnt(0)" ::: "memory");
;         }
;     }
;     __syncthreads();
; __global__ void __launch_bounds__(NWAVES * 64, 2) mk_fwd(Args args) {
;     ...
;         SEAM(p + 4);
.LBB0_544:
	v_readlane_b32 s0, v254, 51
	s_add_i32 s0, s0, 5
	s_cmp_lt_i32 s0, s57
	s_cselect_b64 s[6:7], -1, 0
	s_and_b64 s[2:3], s[4:5], s[6:7]
	s_andn2_b64 vcc, exec, s[2:3]
	s_cbranch_vccnz .LBB0_598
	s_waitcnt vmcnt(0)
	s_waitcnt vmcnt(0) lgkmcnt(0)
	s_barrier
	s_mov_b64 s[4:5], exec
	s_add_u32 s100, s100, 4
	v_readlane_b32 s2, v252, 11
	v_readlane_b32 s3, v252, 12
	s_and_b64 s[2:3], s[4:5], s[2:3]
	s_mov_b64 exec, s[2:3]
	s_cbranch_execz .Llb4_done
	v_mov_b32_e32 v2, 0
	v_mov_b32_e32 v3, 1
	s_and_b32 s3, s100, 3
	s_and_b32 s2, s100, -4
	s_cmp_lg_u32 s3, 0
	s_cbranch_scc1 .Llb4_haveflag
	global_load_dword v4, v2, s[98:99] offset:128 sc1
	s_waitcnt vmcnt(0)
	v_readfirstlane_b32 s8, v4
	s_bcnt1_i32_b32 s8, s8
	s_cmp_eq_u32 s8, 1
	s_cselect_b32 s3, 1, 2
	s_or_b32 s100, s100, s3
.Llb4_haveflag:
	s_cmp_eq_u32 s3, 1
	s_cbranch_scc1 .Llb4_fast
	buffer_wbl2 sc1
	s_waitcnt vmcnt(0)
	global_atomic_add v2, v3, s[98:99]
	s_mov_b32 s8, 0
.Llb4_slowspin:
	global_load_dword v4, v2, s[98:99] sc1
	s_waitcnt vmcnt(0)
	v_readfirstlane_b32 s9, v4
	s_cmp_ge_u32 s9, s2
	s_cbranch_scc1 .Llb4_slowinv
	s_sleep 1
	s_add_u32 s8, s8, 1
	s_cmp_lt_u32 s8, 0x10000
	s_cbranch_scc1 .Llb4_slowspin

; __device__ __forceinline__ void p0_transpose_item(const float* W, int ldw, int col0, int K, bf16* WT, int drow, const float* gain, LAS float* scr, int kb, int nb, int lane) {
;     ...
;     { float v[32]; const float* wp = W + (size_t)(k0 + (lane >> 5)) * ldw + col0 + n0 + (lane & 31);
; #pragma unroll
;       for (int i = 0; i < 32; ++i) v[i] = wp[(size_t)(2 * i) * ldw];
;       if (gain) {
; #pragma unroll
;           for (int i = 0; i < 32; ++i) v[i] *= gain[k0 + 2 * i + (lane >> 5)]; }
; #pragma unroll
;       for (int i = 0; i < 32; ++i) scr[(2 * i + (lane >> 5)) * 33 + (lane & 31)] = v[i]; }
; __device__ __forceinline__ void convert_layer(Frame& F, const In& I, unsigned char* ws, int layer, int widx, int nw) {
;     ...
;             if (layer & 1) { const int kb = r >> 5, nb = r & 31;
;                 p0_transpose_item(I.four_w_out + (size_t)j * 1024 * 1024, 1024, 0, 1024, Wfo + (size_t)j * 1024 * 1024, 32 * nb, nullptr, scr, kb, nb, F.lane); continue; }
.LBB0_647:
	s_andn2_b64 vcc, exec, s[6:7]
	s_cbranch_vccnz .LBB0_625
	s_and_b32 s6, s14, 0xffffffc0
	s_ashr_i32 s7, s6, 31
	s_and_b32 s8, s16, 0x3e0
	s_bfe_u32 s0, s6, 0x10006
	s_lshl_b32 s0, s0, 5
	s_and_b32 s101, s6, 0xffffff80
	s_add_i32 s101, s101, s0
	v_add_u32_e32 v100, s101, v3
	s_lshl_b32 s0, s0, 1
	s_sub_i32 s101, s101, s0
	s_add_i32 s101, s101, 0x61
	v_add_u32_e32 v102, s101, v3
	v_mov_b32_e32 v101, 0
	v_mov_b32_e32 v103, 0
	v_lshlrev_b64 v[100:101], 12, v[100:101]
	v_lshlrev_b64 v[102:103], 12, v[102:103]
	v_lshl_add_u64 v[100:101], s[60:61], 0, v[100:101]
	v_lshl_add_u64 v[102:103], s[60:61], 0, v[102:103]
	s_lshl_b32 s0, s8, 2
	v_lshlrev_b32_e32 v166, 2, v2
	v_lshl_add_u64 v[100:101], v[100:101], 0, s[0:1]
	v_lshl_add_u64 v[102:103], v[102:103], 0, s[0:1]
	v_lshl_add_u64 v[100:101], v[100:101], 0, v[166:167]
	v_lshl_add_u64 v[102:103], v[102:103], 0, v[166:167]
	s_bitcmp0_b32 s6, 6
	s_cselect_b32 s101, 0x40000, 0
	v_mul_u32_u24_e32 v106, s101, v3
	v_sub_u32_e32 v106, 0, v106
	v_ashrrev_i32_e32 v107, 31, v106
	global_load_dword v18, v[100:101], off
	s_mov_b32 s0, 0x2000
	v_lshl_add_u64 v[104:105], v[100:101], 0, s[0:1]
	global_load_dword v19, v[104:105], off
	s_mov_b32 s0, 0x1c000
	v_lshl_add_u64 v[104:105], v[102:103], 0, s[0:1]
	global_load_dword v20, v[104:105], off
	s_mov_b32 s0, 0x1e000
	v_lshl_add_u64 v[104:105], v[102:103], 0, s[0:1]
	v_lshl_add_u64 v[104:105], v[104:105], 0, v[106:107]
	global_load_dword v21, v[104:105], off
	s_mov_b32 s0, 0x4000
	v_lshl_add_u64 v[104:105], v[100:101], 0, s[0:1]
	global_load_dword v22, v[104:105], off
	s_mov_b32 s0, 0x6000
	v_lshl_add_u64 v[104:105], v[100:101], 0, s[0:1]
	global_load_dword v23, v[104:105], off
	s_mov_b32 s0, 0x18000
	v_lshl_add_u64 v[104:105], v[102:103], 0, s[0:1]
	global_load_dword v24, v[104:105], off
	s_mov_b32 s0, 0x1a000
	v_lshl_add_u64 v[104:105], v[102:103], 0, s[0:1]
	global_load_dword v25, v[104:105], off
	s_mov_b32 s0, 0x8000
	v_lshl_add_u64 v[104:105], v[100:101], 0, s[0:1]
	global_load_dword v26, v[104:105], off
	s_mov_b32 s0, 0xa000
	v_lshl_add_u64 v[104:105], v[100:101], 0, s[0:1]
	global_load_dword v27, v[104:105], off
	s_mov_b32 s0, 0x14000
	v_lshl_add_u64 v[104:105], v[102:103], 0, s[0:1]
	global_load_dword v28, v[104:105], off
	s_mov_b32 s0, 0x16000
	v_lshl_add_u64 v[104:105], v[102:103], 0, s[0:1]
	global_load_dword v29, v[104:105], off
	s_mov_b32 s0, 0xc000
	v_lshl_add_u64 v[104:105], v[100:101], 0, s[0:1]
	global_load_dword v30, v[104:105], off
	s_mov_b32 s0, 0xe000
	v_lshl_add_u64 v[104:105], v[100:101], 0, s[0:1]
	global_load_dword v31, v[104:105], off
	s_mov_b32 s0, 0x10000
	v_lshl_add_u64 v[104:105], v[102:103], 0, s[0:1]
	global_load_dword v32, v[104:105], off
	s_mov_b32 s0, 0x12000
	v_lshl_add_u64 v[104:105], v[102:103], 0, s[0:1]
	global_load_dword v33, v[104:105], off
	s_mov_b32 s0, 0x10000
	v_lshl_add_u64 v[104:105], v[100:101], 0, s[0:1]
	global_load_dword v34, v[104:105], off
	s_mov_b32 s0, 0x12000
	v_lshl_add_u64 v[104:105], v[100:101], 0, s[0:1]
	global_load_dword v35, v[104:105], off
	s_mov_b32 s0, 0xc000
	v_lshl_add_u64 v[104:105], v[102:103], 0, s[0:1]
	global_load_dword v36, v[104:105], off
	s_mov_b32 s0, 0xe000
	v_lshl_add_u64 v[104:105], v[102:103], 0, s[0:1]
	global_load_dword v37, v[104:105], off
	s_mov_b32 s0, 0x14000
	v_lshl_add_u64 v[104:105], v[100:101], 0, s[0:1]
	global_load_dword v38, v[104:105], off
	s_mov_b32 s0, 0x16000
	v_lshl_add_u64 v[104:105], v[100:101], 0, s[0:1]
	global_load_dword v39, v[104:105], off
	s_mov_b32 s0, 0x8000
	v_lshl_add_u64 v[104:105], v[102:103], 0, s[0:1]
	global_load_dword v40, v[104:105], off
	s_mov_b32 s0, 0xa000
	v_lshl_add_u64 v[104:105], v[102:103], 0, s[0:1]
	global_load_dword v41, v[104:105], off
	s_mov_b32 s0, 0x18000
	v_lshl_add_u64 v[104:105], v[100:101], 0, s[0:1]
	global_load_dword v42, v[104:105], off
	s_mov_b32 s0, 0x1a000
	v_lshl_add_u64 v[104:105], v[100:101], 0, s[0:1]
	global_load_dword v43, v[104:105], off
	s_mov_b32 s0, 0x4000
	v_lshl_add_u64 v[104:105], v[102:103], 0, s[0:1]
	global_load_dword v44, v[104:105], off
	s_mov_b32 s0, 0x6000
	v_lshl_add_u64 v[104:105], v[102:103], 0, s[0:1]
	global_load_dword v45, v[104:105], off
	s_mov_b32 s0, 0x1c000
	v_lshl_add_u64 v[104:105], v[100:101], 0, s[0:1]
	global_load_dword v46, v[104:105], off
	s_mov_b32 s0, 0x1e000
	v_lshl_add_u64 v[104:105], v[100:101], 0, s[0:1]
	global_load_dword v47, v[104:105], off
	global_load_dword v16, v[102:103], off
	s_mov_b32 s0, 0x2000
	v_lshl_add_u64 v[104:105], v[102:103], 0, s[0:1]
	global_load_dword v14, v[104:105], off
	v_add_u32_e32 v15, 0x400, v50
	s_waitcnt vmcnt(0)
	ds_write2_b32 v50, v18, v19 offset1:66
	ds_write2_b32 v50, v20, v21 offset0:132 offset1:198
	ds_write2_b32 v15, v22, v23 offset0:8 offset1:74
	ds_write2_b32 v15, v24, v25 offset0:140 offset1:206
	v_add_u32_e32 v15, 0x800, v50
	ds_write2_b32 v15, v26, v27 offset0:16 offset1:82
	ds_write2_b32 v15, v28, v29 offset0:148 offset1:214
	v_add_u32_e32 v15, 0xc00, v50
	ds_write2_b32 v15, v30, v31 offset0:24 offset1:90
	ds_write2_b32 v15, v32, v33 offset0:156 offset1:222
	v_add_u32_e32 v15, 0x1000, v50
	ds_write2_b32 v15, v34, v35 offset0:32 offset1:98
	ds_write2_b32 v15, v36, v37 offset0:164 offset1:230
	v_add_u32_e32 v15, 0x1400, v50
	ds_write2_b32 v15, v38, v39 offset0:40 offset1:106
	ds_write2_b32 v15, v40, v41 offset0:172 offset1:238
	v_add_u32_e32 v15, 0x1800, v50
	ds_write2_b32 v15, v42, v43 offset0:48 offset1:114
	ds_write2_b32 v15, v44, v45 offset0:180 offset1:246
	v_add_u32_e32 v15, 0x1c00, v50
	ds_write2_b32 v15, v46, v47 offset0:56 offset1:122
	ds_write2_b32 v15, v16, v14 offset0:188 offset1:254
	s_waitcnt lgkmcnt(0)
; #define GAS __attribute__((address_space(1)))
; #define LAS __attribute__((address_space(3)))
; #define LDS_WAIT() asm volatile("s_waitcnt lgkmcnt(0)" ::: "memory")
; __device__ __forceinline__ unsigned pk2(float lo, float hi) { return f2bf(lo) | (f2bf(hi) << 16); }
; __device__ __forceinline__ void p0_transpose_item(const float* W, int ldw, int col0, int K, bf16* WT, int drow, const float* gain, LAS float* scr, int kb, int nb, int lane) {
;     ...
;     LDS_WAIT(); asm volatile("" ::: "memory");
;     const int c = lane & 7;
; #pragma unroll
;     for (int j = 0; j < 4; ++j) { const int n = (lane >> 3) + 8 * j; const LAS float* s = scr + (8 * c) * 33 + n;
;         v4u o; o.x = pk2(s[0 * 33], s[1 * 33]); o.y = pk2(s[2 * 33], s[3 * 33]); o.z = pk2(s[4 * 33], s[5 * 33]); o.w = pk2(s[6 * 33], s[7 * 33]);
;         *(GAS v4u*)(WT + (size_t)(drow + n) * K + k0 + 8 * c) = o; }
;     LDS_WAIT(); asm volatile("" ::: "memory");
	ds_read2_b32 v[20:21], v52 offset0:33 offset1:41
	ds_read2_b32 v[22:23], v52 offset1:8
	ds_read2_b32 v[24:25], v52 offset0:66 offset1:74
	ds_read2_b32 v[26:27], v52 offset0:99 offset1:107
	v_lshl_add_u64 v[14:15], s[6:7], 1, v[12:13]
	s_movk_i32 s6, 0x7fff
	s_waitcnt lgkmcnt(3)
	v_bfe_u32 v17, v20, 16, 1
	s_waitcnt lgkmcnt(2)
	v_bfe_u32 v16, v22, 16, 1
	v_add3_u32 v16, v22, v16, s6
	v_lshrrev_b32_e32 v16, 16, v16
	v_add3_u32 v17, v20, v17, s6
	s_mov_b32 s0, 0xffff0000
	ds_read2_b32 v[28:29], v52 offset0:132 offset1:140
	ds_read2_b32 v[30:31], v52 offset0:165 offset1:173
	v_and_or_b32 v16, v17, s0, v16
	s_waitcnt lgkmcnt(3)
	v_bfe_u32 v17, v24, 16, 1
	v_add3_u32 v17, v24, v17, s6
	s_waitcnt lgkmcnt(2)
	v_bfe_u32 v18, v26, 16, 1
	v_lshrrev_b32_e32 v17, 16, v17
	v_add3_u32 v18, v26, v18, s6
	ds_read2_b32 v[32:33], v52 offset0:198 offset1:206
	ds_read2_b32 v[34:35], v52 offset0:231 offset1:239
	v_and_or_b32 v17, v18, s0, v17
	s_waitcnt lgkmcnt(3)
	v_bfe_u32 v18, v28, 16, 1
	v_add3_u32 v18, v28, v18, s6
	s_waitcnt lgkmcnt(2)
	v_bfe_u32 v19, v30, 16, 1
	v_lshrrev_b32_e32 v18, 16, v18
	v_add3_u32 v19, v30, v19, s6
	v_and_or_b32 v18, v19, s0, v18
	s_waitcnt lgkmcnt(1)
	v_bfe_u32 v19, v32, 16, 1
	v_add3_u32 v19, v32, v19, s6
	s_waitcnt lgkmcnt(0)
	v_bfe_u32 v20, v34, 16, 1
	v_lshrrev_b32_e32 v19, 16, v19
	v_add3_u32 v20, v34, v20, s6
	v_and_or_b32 v19, v20, s0, v19
	v_or_b32_e32 v20, s8, v51
	v_lshlrev_b32_e32 v166, 11, v20
	v_lshl_add_u64 v[36:37], v[14:15], 0, v[166:167]
	global_store_dwordx4 v[36:37], v[16:19], off
	v_bfe_u32 v20, v35, 16, 1
	v_add3_u32 v20, v35, v20, s6
	v_bfe_u32 v16, v23, 16, 1
	v_add3_u32 v16, v23, v16, s6
	v_bfe_u32 v17, v21, 16, 1
	v_lshrrev_b32_e32 v16, 16, v16
	v_add3_u32 v17, v21, v17, s6
	v_and_or_b32 v16, v17, s0, v16
	v_bfe_u32 v17, v25, 16, 1
	v_add3_u32 v17, v25, v17, s6
	v_bfe_u32 v18, v27, 16, 1
	v_lshrrev_b32_e32 v17, 16, v17
	v_add3_u32 v18, v27, v18, s6
	v_and_or_b32 v17, v18, s0, v17
	v_bfe_u32 v18, v29, 16, 1
	v_add3_u32 v18, v29, v18, s6
	v_bfe_u32 v19, v31, 16, 1
	v_lshrrev_b32_e32 v18, 16, v18
	v_add3_u32 v19, v31, v19, s6
	v_and_or_b32 v18, v19, s0, v18
	v_bfe_u32 v19, v33, 16, 1
	v_add3_u32 v19, v33, v19, s6
	v_lshrrev_b32_e32 v19, 16, v19
	v_and_or_b32 v19, v20, s0, v19
	v_or_b32_e32 v20, s8, v53
	v_lshlrev_b32_e32 v166, 11, v20
	v_lshl_add_u64 v[20:21], v[14:15], 0, v[166:167]
	global_store_dwordx4 v[20:21], v[16:19], off
	ds_read2_b32 v[20:21], v52 offset0:49 offset1:57
	ds_read2_b32 v[22:23], v52 offset0:16 offset1:24
	ds_read2_b32 v[24:25], v52 offset0:82 offset1:90
	ds_read2_b32 v[26:27], v52 offset0:115 offset1:123
	ds_read2_b32 v[28:29], v52 offset0:148 offset1:156
	ds_read2_b32 v[30:31], v52 offset0:181 offset1:189
	ds_read2_b32 v[32:33], v52 offset0:214 offset1:222
	ds_read2_b32 v[34:35], v52 offset0:247 offset1:255
	s_waitcnt lgkmcnt(7)
	v_bfe_u32 v17, v20, 16, 1
	s_waitcnt lgkmcnt(6)
	v_bfe_u32 v16, v22, 16, 1
	v_add3_u32 v16, v22, v16, s6
	v_lshrrev_b32_e32 v16, 16, v16
	v_add3_u32 v17, v20, v17, s6
	v_and_or_b32 v16, v17, s0, v16
	s_waitcnt lgkmcnt(5)
	v_bfe_u32 v17, v24, 16, 1
	v_add3_u32 v17, v24, v17, s6
	s_waitcnt lgkmcnt(4)
	v_bfe_u32 v18, v26, 16, 1
	v_lshrrev_b32_e32 v17, 16, v17
	v_add3_u32 v18, v26, v18, s6
	v_and_or_b32 v17, v18, s0, v17
	s_waitcnt lgkmcnt(3)
	v_bfe_u32 v18, v28, 16, 1
	v_add3_u32 v18, v28, v18, s6
	s_waitcnt lgkmcnt(2)
	v_bfe_u32 v19, v30, 16, 1
	v_lshrrev_b32_e32 v18, 16, v18
	v_add3_u32 v19, v30, v19, s6
	v_and_or_b32 v18, v19, s0, v18
	s_waitcnt lgkmcnt(1)
	v_bfe_u32 v19, v32, 16, 1
	v_add3_u32 v19, v32, v19, s6
	s_waitcnt lgkmcnt(0)
	v_bfe_u32 v20, v34, 16, 1
	v_lshrrev_b32_e32 v19, 16, v19
	v_add3_u32 v20, v34, v20, s6
	v_and_or_b32 v19, v20, s0, v19
	v_or_b32_e32 v20, s8, v54
	v_lshlrev_b32_e32 v166, 11, v20
	v_lshl_add_u64 v[36:37], v[14:15], 0, v[166:167]
	global_store_dwordx4 v[36:37], v[16:19], off
	v_bfe_u32 v20, v35, 16, 1
	v_add3_u32 v20, v35, v20, s6
	v_bfe_u32 v16, v23, 16, 1
	v_add3_u32 v16, v23, v16, s6
	v_bfe_u32 v17, v21, 16, 1
	v_lshrrev_b32_e32 v16, 16, v16
	v_add3_u32 v17, v21, v17, s6
	v_and_or_b32 v16, v17, s0, v16
	v_bfe_u32 v17, v25, 16, 1
	v_add3_u32 v17, v25, v17, s6
	v_bfe_u32 v18, v27, 16, 1
	v_lshrrev_b32_e32 v17, 16, v17
	v_add3_u32 v18, v27, v18, s6
	v_and_or_b32 v17, v18, s0, v17
	v_bfe_u32 v18, v29, 16, 1
	v_add3_u32 v18, v29, v18, s6
	v_bfe_u32 v19, v31, 16, 1
	v_lshrrev_b32_e32 v18, 16, v18
	v_add3_u32 v19, v31, v19, s6
	v_and_or_b32 v18, v19, s0, v18
	v_bfe_u32 v19, v33, 16, 1
	v_add3_u32 v19, v33, v19, s6
	v_lshrrev_b32_e32 v19, 16, v19
	v_and_or_b32 v19, v20, s0, v19
	v_or_b32_e32 v20, s8, v55
	v_lshlrev_b32_e32 v166, 11, v20
	v_lshl_add_u64 v[14:15], v[14:15], 0, v[166:167]
	global_store_dwordx4 v[14:15], v[16:19], off
	s_waitcnt lgkmcnt(0)
	s_branch .LBB0_625

; __device__ __forceinline__ void p0_transpose_item(const float* W, int ldw, int col0, int K, bf16* WT, int drow, const float* gain, LAS float* scr, int kb, int nb, int lane) {
;     ...
;     { float v[32]; const float* wp = W + (size_t)(k0 + (lane >> 5)) * ldw + col0 + n0 + (lane & 31);
; #pragma unroll
;       for (int i = 0; i < 32; ++i) v[i] = wp[(size_t)(2 * i) * ldw];
;       if (gain) {
; #pragma unroll
;           for (int i = 0; i < 32; ++i) v[i] *= gain[k0 + 2 * i + (lane >> 5)]; }
; #pragma unroll
;       for (int i = 0; i < 32; ++i) scr[(2 * i + (lane >> 5)) * 33 + (lane & 31)] = v[i]; }
; __device__ __forceinline__ void convert_layer(Frame& F, const In& I, unsigned char* ws, int layer, int widx, int nw) {
;     ...
;             if (layer & 1) { const int kb = r >> 5, nb = r & 31;
;                 p0_transpose_item(I.four_w_out + (size_t)j * 1024 * 1024, 1024, 0, 1024, Wfo + (size_t)j * 1024 * 1024, 32 * nb, nullptr, scr, kb, nb, F.lane); continue; }
.LBB0_676:
	s_andn2_b64 vcc, exec, s[6:7]
	s_cbranch_vccnz .LBB0_654
	s_and_b32 s6, s2, 0xffffffc0
	s_ashr_i32 s7, s6, 31
	s_and_b32 s8, s15, 0x3e0
	s_bfe_u32 s0, s6, 0x10006
	s_lshl_b32 s0, s0, 5
	s_and_b32 s101, s6, 0xffffff80
	s_add_i32 s101, s101, s0
	v_add_u32_e32 v100, s101, v3
	s_lshl_b32 s0, s0, 1
	s_sub_i32 s101, s101, s0
	s_add_i32 s101, s101, 0x61
	v_add_u32_e32 v102, s101, v3
	v_mov_b32_e32 v101, 0
	v_mov_b32_e32 v103, 0
	v_lshlrev_b64 v[100:101], 12, v[100:101]
	v_lshlrev_b64 v[102:103], 12, v[102:103]
	v_lshl_add_u64 v[100:101], s[60:61], 0, v[100:101]
	v_lshl_add_u64 v[102:103], s[60:61], 0, v[102:103]
	s_lshl_b32 s0, s8, 2
	v_lshlrev_b32_e32 v166, 2, v2
	v_lshl_add_u64 v[100:101], v[100:101], 0, s[0:1]
	v_lshl_add_u64 v[102:103], v[102:103], 0, s[0:1]
	v_lshl_add_u64 v[100:101], v[100:101], 0, v[166:167]
	v_lshl_add_u64 v[102:103], v[102:103], 0, v[166:167]
	s_bitcmp0_b32 s6, 6
	s_cselect_b32 s101, 0x40000, 0
	v_mul_u32_u24_e32 v106, s101, v3
	v_sub_u32_e32 v106, 0, v106
	v_ashrrev_i32_e32 v107, 31, v106
	global_load_dword v18, v[100:101], off
	s_mov_b32 s0, 0x2000
	v_lshl_add_u64 v[104:105], v[100:101], 0, s[0:1]
	global_load_dword v19, v[104:105], off
	s_mov_b32 s0, 0x1c000
	v_lshl_add_u64 v[104:105], v[102:103], 0, s[0:1]
	global_load_dword v20, v[104:105], off
	s_mov_b32 s0, 0x1e000
	v_lshl_add_u64 v[104:105], v[102:103], 0, s[0:1]
	v_lshl_add_u64 v[104:105], v[104:105], 0, v[106:107]
	global_load_dword v21, v[104:105], off
	s_mov_b32 s0, 0x4000
	v_lshl_add_u64 v[104:105], v[100:101], 0, s[0:1]
	global_load_dword v22, v[104:105], off
	s_mov_b32 s0, 0x6000
	v_lshl_add_u64 v[104:105], v[100:101], 0, s[0:1]
	global_load_dword v23, v[104:105], off
	s_mov_b32 s0, 0x18000
	v_lshl_add_u64 v[104:105], v[102:103], 0, s[0:1]
	global_load_dword v24, v[104:105], off
	s_mov_b32 s0, 0x1a000
	v_lshl_add_u64 v[104:105], v[102:103], 0, s[0:1]
	global_load_dword v25, v[104:105], off
	s_mov_b32 s0, 0x8000
	v_lshl_add_u64 v[104:105], v[100:101], 0, s[0:1]
	global_load_dword v26, v[104:105], off
	s_mov_b32 s0, 0xa000
	v_lshl_add_u64 v[104:105], v[100:101], 0, s[0:1]
	global_load_dword v27, v[104:105], off
	s_mov_b32 s0, 0x14000
	v_lshl_add_u64 v[104:105], v[102:103], 0, s[0:1]
	global_load_dword v28, v[104:105], off
	s_mov_b32 s0, 0x16000
	v_lshl_add_u64 v[104:105], v[102:103], 0, s[0:1]
	global_load_dword v29, v[104:105], off
	s_mov_b32 s0, 0xc000
	v_lshl_add_u64 v[104:105], v[100:101], 0, s[0:1]
	global_load_dword v30, v[104:105], off
	s_mov_b32 s0, 0xe000
	v_lshl_add_u64 v[104:105], v[100:101], 0, s[0:1]
	global_load_dword v31, v[104:105], off
	s_mov_b32 s0, 0x10000
	v_lshl_add_u64 v[104:105], v[102:103], 0, s[0:1]
	global_load_dword v32, v[104:105], off
	s_mov_b32 s0, 0x12000
	v_lshl_add_u64 v[104:105], v[102:103], 0, s[0:1]
	global_load_dword v33, v[104:105], off
	s_mov_b32 s0, 0x10000
	v_lshl_add_u64 v[104:105], v[100:101], 0, s[0:1]
	global_load_dword v34, v[104:105], off
	s_mov_b32 s0, 0x12000
	v_lshl_add_u64 v[104:105], v[100:101], 0, s[0:1]
	global_load_dword v35, v[104:105], off
	s_mov_b32 s0, 0xc000
	v_lshl_add_u64 v[104:105], v[102:103], 0, s[0:1]
	global_load_dword v36, v[104:105], off
	s_mov_b32 s0, 0xe000
	v_lshl_add_u64 v[104:105], v[102:103], 0, s[0:1]
	global_load_dword v37, v[104:105], off
	s_mov_b32 s0, 0x14000
	v_lshl_add_u64 v[104:105], v[100:101], 0, s[0:1]
	global_load_dword v38, v[104:105], off
	s_mov_b32 s0, 0x16000
	v_lshl_add_u64 v[104:105], v[100:101], 0, s[0:1]
	global_load_dword v39, v[104:105], off
	s_mov_b32 s0, 0x8000
	v_lshl_add_u64 v[104:105], v[102:103], 0, s[0:1]
	global_load_dword v40, v[104:105], off
	s_mov_b32 s0, 0xa000
	v_lshl_add_u64 v[104:105], v[102:103], 0, s[0:1]
	global_load_dword v41, v[104:105], off
	s_mov_b32 s0, 0x18000
	v_lshl_add_u64 v[104:105], v[100:101], 0, s[0:1]
	global_load_dword v42, v[104:105], off
	s_mov_b32 s0, 0x1a000
	v_lshl_add_u64 v[104:105], v[100:101], 0, s[0:1]
	global_load_dword v43, v[104:105], off
	s_mov_b32 s0, 0x4000
	v_lshl_add_u64 v[104:105], v[102:103], 0, s[0:1]
	global_load_dword v44, v[104:105], off
	s_mov_b32 s0, 0x6000
	v_lshl_add_u64 v[104:105], v[102:103], 0, s[0:1]
	global_load_dword v45, v[104:105], off
	s_mov_b32 s0, 0x1c000
	v_lshl_add_u64 v[104:105], v[100:101], 0, s[0:1]
	global_load_dword v46, v[104:105], off
	s_mov_b32 s0, 0x1e000
	v_lshl_add_u64 v[104:105], v[100:101], 0, s[0:1]
	global_load_dword v47, v[104:105], off
	global_load_dword v16, v[102:103], off
	s_mov_b32 s0, 0x2000
	v_lshl_add_u64 v[104:105], v[102:103], 0, s[0:1]
	global_load_dword v14, v[104:105], off
	v_add_u32_e32 v15, 0x400, v50
	s_waitcnt vmcnt(0)
	ds_write2_b32 v50, v18, v19 offset1:66
	ds_write2_b32 v50, v20, v21 offset0:132 offset1:198
	ds_write2_b32 v15, v22, v23 offset0:8 offset1:74
	ds_write2_b32 v15, v24, v25 offset0:140 offset1:206
	v_add_u32_e32 v15, 0x800, v50
	ds_write2_b32 v15, v26, v27 offset0:16 offset1:82
	ds_write2_b32 v15, v28, v29 offset0:148 offset1:214
	v_add_u32_e32 v15, 0xc00, v50
	ds_write2_b32 v15, v30, v31 offset0:24 offset1:90
	ds_write2_b32 v15, v32, v33 offset0:156 offset1:222
	v_add_u32_e32 v15, 0x1000, v50
	ds_write2_b32 v15, v34, v35 offset0:32 offset1:98
	ds_write2_b32 v15, v36, v37 offset0:164 offset1:230
	v_add_u32_e32 v15, 0x1400, v50
	ds_write2_b32 v15, v38, v39 offset0:40 offset1:106
	ds_write2_b32 v15, v40, v41 offset0:172 offset1:238
	v_add_u32_e32 v15, 0x1800, v50
	ds_write2_b32 v15, v42, v43 offset0:48 offset1:114
	ds_write2_b32 v15, v44, v45 offset0:180 offset1:246
	v_add_u32_e32 v15, 0x1c00, v50
	ds_write2_b32 v15, v46, v47 offset0:56 offset1:122
	ds_write2_b32 v15, v16, v14 offset0:188 offset1:254
	s_waitcnt lgkmcnt(0)
; #define GAS __attribute__((address_space(1)))
; #define LAS __attribute__((address_space(3)))
; #define LDS_WAIT() asm volatile("s_waitcnt lgkmcnt(0)" ::: "memory")
; __device__ __forceinline__ unsigned pk2(float lo, float hi) { return f2bf(lo) | (f2bf(hi) << 16); }
; __device__ __forceinline__ void p0_transpose_item(const float* W, int ldw, int col0, int K, bf16* WT, int drow, const float* gain, LAS float* scr, int kb, int nb, int lane) {
;     ...
;     LDS_WAIT(); asm volatile("" ::: "memory");
;     const int c = lane & 7;
; #pragma unroll
;     for (int j = 0; j < 4; ++j) { const int n = (lane >> 3) + 8 * j; const LAS float* s = scr + (8 * c) * 33 + n;
;         v4u o; o.x = pk2(s[0 * 33], s[1 * 33]); o.y = pk2(s[2 * 33], s[3 * 33]); o.z = pk2(s[4 * 33], s[5 * 33]); o.w = pk2(s[6 * 33], s[7 * 33]);
;         *(GAS v4u*)(WT + (size_t)(drow + n) * K + k0 + 8 * c) = o; }
;     LDS_WAIT(); asm volatile("" ::: "memory");
	ds_read2_b32 v[20:21], v52 offset0:33 offset1:41
	ds_read2_b32 v[22:23], v52 offset1:8
	ds_read2_b32 v[24:25], v52 offset0:66 offset1:74
	ds_read2_b32 v[26:27], v52 offset0:99 offset1:107
	v_lshl_add_u64 v[14:15], s[6:7], 1, v[12:13]
	s_movk_i32 s6, 0x7fff
	s_waitcnt lgkmcnt(3)
	v_bfe_u32 v17, v20, 16, 1
	s_waitcnt lgkmcnt(2)
	v_bfe_u32 v16, v22, 16, 1
	v_add3_u32 v16, v22, v16, s6
	v_lshrrev_b32_e32 v16, 16, v16
	v_add3_u32 v17, v20, v17, s6
	s_mov_b32 s0, 0xffff0000
	ds_read2_b32 v[28:29], v52 offset0:132 offset1:140
	ds_read2_b32 v[30:31], v52 offset0:165 offset1:173
	v_and_or_b32 v16, v17, s0, v16
	s_waitcnt lgkmcnt(3)
	v_bfe_u32 v17, v24, 16, 1
	v_add3_u32 v17, v24, v17, s6
	s_waitcnt lgkmcnt(2)
	v_bfe_u32 v18, v26, 16, 1
	v_lshrrev_b32_e32 v17, 16, v17
	v_add3_u32 v18, v26, v18, s6
	ds_read2_b32 v[32:33], v52 offset0:198 offset1:206
	ds_read2_b32 v[34:35], v52 offset0:231 offset1:239
	v_and_or_b32 v17, v18, s0, v17
	s_waitcnt lgkmcnt(3)
	v_bfe_u32 v18, v28, 16, 1
	v_add3_u32 v18, v28, v18, s6
	s_waitcnt lgkmcnt(2)
	v_bfe_u32 v19, v30, 16, 1
	v_lshrrev_b32_e32 v18, 16, v18
	v_add3_u32 v19, v30, v19, s6
	v_and_or_b32 v18, v19, s0, v18
	s_waitcnt lgkmcnt(1)
	v_bfe_u32 v19, v32, 16, 1
	v_add3_u32 v19, v32, v19, s6
	s_waitcnt lgkmcnt(0)
	v_bfe_u32 v20, v34, 16, 1
	v_lshrrev_b32_e32 v19, 16, v19
	v_add3_u32 v20, v34, v20, s6
	v_and_or_b32 v19, v20, s0, v19
	v_or_b32_e32 v20, s8, v51
	v_lshlrev_b32_e32 v166, 11, v20
	v_lshl_add_u64 v[36:37], v[14:15], 0, v[166:167]
	global_store_dwordx4 v[36:37], v[16:19], off
	v_bfe_u32 v20, v35, 16, 1
	v_add3_u32 v20, v35, v20, s6
	v_bfe_u32 v16, v23, 16, 1
	v_add3_u32 v16, v23, v16, s6
	v_bfe_u32 v17, v21, 16, 1
	v_lshrrev_b32_e32 v16, 16, v16
	v_add3_u32 v17, v21, v17, s6
	v_and_or_b32 v16, v17, s0, v16
	v_bfe_u32 v17, v25, 16, 1
	v_add3_u32 v17, v25, v17, s6
	v_bfe_u32 v18, v27, 16, 1
	v_lshrrev_b32_e32 v17, 16, v17
	v_add3_u32 v18, v27, v18, s6
	v_and_or_b32 v17, v18, s0, v17
	v_bfe_u32 v18, v29, 16, 1
	v_add3_u32 v18, v29, v18, s6
	v_bfe_u32 v19, v31, 16, 1
	v_lshrrev_b32_e32 v18, 16, v18
	v_add3_u32 v19, v31, v19, s6
	v_and_or_b32 v18, v19, s0, v18
	v_bfe_u32 v19, v33, 16, 1
	v_add3_u32 v19, v33, v19, s6
	v_lshrrev_b32_e32 v19, 16, v19
	v_and_or_b32 v19, v20, s0, v19
	v_or_b32_e32 v20, s8, v53
	v_lshlrev_b32_e32 v166, 11, v20
	v_lshl_add_u64 v[20:21], v[14:15], 0, v[166:167]
	global_store_dwordx4 v[20:21], v[16:19], off
	ds_read2_b32 v[20:21], v52 offset0:49 offset1:57
	ds_read2_b32 v[22:23], v52 offset0:16 offset1:24
	ds_read2_b32 v[24:25], v52 offset0:82 offset1:90
	ds_read2_b32 v[26:27], v52 offset0:115 offset1:123
	ds_read2_b32 v[28:29], v52 offset0:148 offset1:156
	ds_read2_b32 v[30:31], v52 offset0:181 offset1:189
	ds_read2_b32 v[32:33], v52 offset0:214 offset1:222
	ds_read2_b32 v[34:35], v52 offset0:247 offset1:255
	s_waitcnt lgkmcnt(7)
	v_bfe_u32 v17, v20, 16, 1
	s_waitcnt lgkmcnt(6)
	v_bfe_u32 v16, v22, 16, 1
	v_add3_u32 v16, v22, v16, s6
	v_lshrrev_b32_e32 v16, 16, v16
	v_add3_u32 v17, v20, v17, s6
	v_and_or_b32 v16, v17, s0, v16
	s_waitcnt lgkmcnt(5)
	v_bfe_u32 v17, v24, 16, 1
	v_add3_u32 v17, v24, v17, s6
	s_waitcnt lgkmcnt(4)
	v_bfe_u32 v18, v26, 16, 1
	v_lshrrev_b32_e32 v17, 16, v17
	v_add3_u32 v18, v26, v18, s6
	v_and_or_b32 v17, v18, s0, v17
	s_waitcnt lgkmcnt(3)
	v_bfe_u32 v18, v28, 16, 1
	v_add3_u32 v18, v28, v18, s6
	s_waitcnt lgkmcnt(2)
	v_bfe_u32 v19, v30, 16, 1
	v_lshrrev_b32_e32 v18, 16, v18
	v_add3_u32 v19, v30, v19, s6
	v_and_or_b32 v18, v19, s0, v18
	s_waitcnt lgkmcnt(1)
	v_bfe_u32 v19, v32, 16, 1
	v_add3_u32 v19, v32, v19, s6
	s_waitcnt lgkmcnt(0)
	v_bfe_u32 v20, v34, 16, 1
	v_lshrrev_b32_e32 v19, 16, v19
	v_add3_u32 v20, v34, v20, s6
	v_and_or_b32 v19, v20, s0, v19
	v_or_b32_e32 v20, s8, v54
	v_lshlrev_b32_e32 v166, 11, v20
	v_lshl_add_u64 v[36:37], v[14:15], 0, v[166:167]
	global_store_dwordx4 v[36:37], v[16:19], off
	v_bfe_u32 v20, v35, 16, 1
	v_add3_u32 v20, v35, v20, s6
	v_bfe_u32 v16, v23, 16, 1
	v_add3_u32 v16, v23, v16, s6
	v_bfe_u32 v17, v21, 16, 1
	v_lshrrev_b32_e32 v16, 16, v16
	v_add3_u32 v17, v21, v17, s6
	v_and_or_b32 v16, v17, s0, v16
	v_bfe_u32 v17, v25, 16, 1
	v_add3_u32 v17, v25, v17, s6
	v_bfe_u32 v18, v27, 16, 1
	v_lshrrev_b32_e32 v17, 16, v17
	v_add3_u32 v18, v27, v18, s6
	v_and_or_b32 v17, v18, s0, v17
	v_bfe_u32 v18, v29, 16, 1
	v_add3_u32 v18, v29, v18, s6
	v_bfe_u32 v19, v31, 16, 1
	v_lshrrev_b32_e32 v18, 16, v18
	v_add3_u32 v19, v31, v19, s6
	v_and_or_b32 v18, v19, s0, v18
	v_bfe_u32 v19, v33, 16, 1
	v_add3_u32 v19, v33, v19, s6
	v_lshrrev_b32_e32 v19, 16, v19
	v_and_or_b32 v19, v20, s0, v19
	v_or_b32_e32 v20, s8, v55
	v_lshlrev_b32_e32 v166, 11, v20
	v_lshl_add_u64 v[14:15], v[14:15], 0, v[166:167]
	global_store_dwordx4 v[14:15], v[16:19], off
	s_waitcnt lgkmcnt(0)
	s_branch .LBB0_654

; __device__ __forceinline__ unsigned xb_ld(unsigned* p)              { return __hip_atomic_load(p, __ATOMIC_RELAXED, __HIP_MEMORY_SCOPE_AGENT); }
; __device__ __forceinline__ unsigned xb_add(unsigned* p, unsigned v) { return __hip_atomic_fetch_add(p, v, __ATOMIC_RELAXED, __HIP_MEMORY_SCOPE_AGENT); }
; #define XB_SPIN(cond, bar) do { unsigned _sp = 0; while (cond) { __builtin_amdgcn_s_sleep(1); \
;     if ((++_sp & 255u) == 0u) { if (xb_ld(&(bar)[XB_TMO])) break; if (_sp > XB_SPIN_CAP) { atomicAdd(&(bar)[XB_TMO], 1u); break; } } } } while (0)
; #define SEAM(k) do { if (!MK_PER_PHASE && IN(k) && IN((k) + 1)) xcd_barrier(bar); } while (0)
; __device__ __forceinline__ void xcd_barrier(const XcdBarrier& b) {
;     asm volatile("s_waitcnt vmcnt(0)" ::: "memory");
;     __syncthreads();
;     if (threadIdx.x == 0) {
;         unsigned* bar = b.bar;
;         __builtin_amdgcn_s_waitcnt(0);
;         unsigned nloc = b.st[0], nx = b.st[1];
;         if (nloc == 0u) { xcd_barrier_complete(bar, b.x, nloc, nx); b.st[0] = nloc; b.st[1] = nx; }
;         const unsigned old = xb_add(&bar[XB_XSUB(b.x)], 1u);
;         const unsigned gen = old / nloc;
;         if (old + 1u == (gen + 1u) * nloc) {
;             __builtin_amdgcn_fence(__ATOMIC_RELEASE, "agent");
;             asm volatile("s_waitcnt vmcnt(0)" ::: "memory");
;             const unsigned og = xb_add(&bar[XB_TOP], 1u);
;             const unsigned tg = og / nx;
;             if (og + 1u == (tg + 1u) * nx) xb_add(&bar[XB_TOPGEN], 1u);
;             else XB_SPIN(xb_ld(&bar[XB_TOPGEN]) == tg, bar);
;             __builtin_amdgcn_fence(__ATOMIC_ACQUIRE, "agent");
;             xb_add(&bar[XB_XGEN(b.x)], 1u);
;             asm volatile("s_waitcnt vmcnt(0)" ::: "memory");
;         } else {
;             XB_SPIN(xb_ld(&bar[XB_XGEN(b.x)]) == gen, bar);
;             __builtin_amdgcn_fence(__ATOMIC_ACQUIRE, "agent");
;             asm volatile("s_waitcnt vmcnt(0)" ::: "memory");
;         }
;     }
;     __syncthreads();
; __global__ void __launch_bounds__(NWAVES * 64, 2) mk_fwd(Args args) {
;     ...
;         SEAM(p + 5);
.LBB0_679:
	v_readlane_b32 s0, v254, 51
	s_add_i32 s0, s0, 6
	s_cmp_lt_i32 s0, s57
	s_cselect_b64 s[4:5], -1, 0
	s_and_b64 s[2:3], s[42:43], s[4:5]
	s_andn2_b64 vcc, exec, s[2:3]
	s_cbranch_vccnz .LBB0_733
	s_waitcnt vmcnt(0)
	s_waitcnt vmcnt(0) lgkmcnt(0)
	s_barrier
	s_mov_b64 s[6:7], exec
	s_add_u32 s100, s100, 4
	v_readlane_b32 s2, v252, 11
	v_readlane_b32 s3, v252, 12
	s_and_b64 s[2:3], s[6:7], s[2:3]
	s_mov_b64 exec, s[2:3]
	s_cbranch_execz .Llb5_done
	v_mov_b32_e32 v2, 0
	v_mov_b32_e32 v3, 1
	s_and_b32 s3, s100, 3
	s_and_b32 s2, s100, -4
	s_cmp_lg_u32 s3, 0
	s_cbranch_scc1 .Llb5_haveflag
	global_load_dword v4, v2, s[98:99] offset:128 sc1
	s_waitcnt vmcnt(0)
	v_readfirstlane_b32 s8, v4
	s_bcnt1_i32_b32 s8, s8
	s_cmp_eq_u32 s8, 1
	s_cselect_b32 s3, 1, 2
	s_or_b32 s100, s100, s3
